# v98 + P5: next-gate tuples of 4 of the 16 items stay in spare VGPRs across the following K-loop (25 pct fewer current-gate re-reads)
# speedup vs baseline: 1.0200x; 1.0000x over previous
.LBB0_793:
	s_lshl_b32 s2, s47, 8
	v_readlane_b32 s3, v253, 62
	s_add_i32 s2, s2, s3
	v_add_u32_e32 v250, s2, v194
	s_lshl_b32 s2, s46, 8
	v_readlane_b32 s3, v254, 18
	s_or_b32 s2, s2, s3
	v_lshl_add_u32 v251, v195, 3, s2
	v_lshlrev_b32_e32 v251, 1, v251
	v_lshl_add_u32 v248, v250, 13, v251
	v_lshl_add_u32 v249, v250, 11, v251
	s_lshl_b32 s0, s45, 11
	s_add_u32 s0, s4, s0
	s_addc_u32 s1, s5, 0
	s_mov_b64 s[56:57], s[0:1]
	s_mov_b64 s[82:83], s[6:7]
	s_add_u32 s58, s0, 0x20000
	s_addc_u32 s59, s1, 0
	s_add_u32 s84, s6, 0x8000
	s_addc_u32 s85, s7, 0
	s_add_u32 s60, s0, 0x40000
	s_addc_u32 s61, s1, 0
	s_add_u32 s86, s6, 0x10000
	s_addc_u32 s87, s7, 0
	s_add_u32 s62, s0, 0x60000
	s_addc_u32 s63, s1, 0
	s_add_u32 s88, s6, 0x18000
	s_addc_u32 s89, s7, 0
	s_add_u32 s64, s0, 0x100000
	s_addc_u32 s65, s1, 0
	s_add_u32 s90, s6, 0x40000
	s_addc_u32 s91, s7, 0
	s_add_u32 s66, s0, 0x120000
	s_addc_u32 s67, s1, 0
	s_add_u32 s92, s6, 0x48000
	s_addc_u32 s93, s7, 0
	s_add_u32 s68, s0, 0x140000
	s_addc_u32 s69, s1, 0
	s_add_u32 s94, s6, 0x50000
	s_addc_u32 s95, s7, 0
	s_add_u32 s70, s0, 0x160000
	s_addc_u32 s71, s1, 0
	s_add_u32 s96, s6, 0x58000
	s_addc_u32 s97, s7, 0
	s_cmp_eq_u32 s45, 3
	s_cbranch_scc1 .Lm_final
	s_cmp_eq_u32 s45, 0
	s_cbranch_scc0 .Lm_mid
	global_load_dwordx4 v[130:133], v248, s[56:57]
	global_load_dwordx4 v[134:137], v248, s[56:57] offset:2048
	global_load_dwordx4 v[138:141], v248, s[56:57] offset:256
	global_load_dwordx4 v[142:145], v248, s[56:57] offset:2304
	global_load_dwordx4 v[146:149], v248, s[58:59]
	global_load_dwordx4 v[150:153], v248, s[58:59] offset:2048
	global_load_dwordx4 v[164:167], v248, s[58:59] offset:256
	global_load_dwordx4 v[168:171], v248, s[58:59] offset:2304
	global_load_dwordx4 v[172:175], v248, s[60:61]
	global_load_dwordx4 v[180:183], v248, s[60:61] offset:2048
	global_load_dwordx4 v[184:187], v248, s[60:61] offset:256
	global_load_dwordx4 v[188:191], v248, s[60:61] offset:2304
	global_load_dwordx4 v[198:201], v248, s[62:63]
	global_load_dwordx4 v[212:215], v248, s[62:63] offset:2048
	global_load_dwordx4 v[216:219], v248, s[62:63] offset:256
	global_load_dwordx4 v[220:223], v248, s[62:63] offset:2304
	global_load_dwordx4 v[224:227], v248, s[64:65]
	global_load_dwordx4 v[228:231], v248, s[64:65] offset:2048
	s_waitcnt vmcnt(16)
	v_lshlrev_b32_e32 v250, 16, v134
	v_and_b32_e32 v251, 0xffff0000, v134
	v_lshlrev_b32_e32 v192, 16, v130
	v_and_b32_e32 v193, 0xffff0000, v130
	v_max_f32_e32 v250, 0x0da24260, v250
	v_max_f32_e32 v251, 0x0da24260, v251
	v_rcp_f32_e32 v250, v250
	v_rcp_f32_e32 v251, v251
	v_max_f32_e32 v192, 0x0da24260, v192
	v_max_f32_e32 v193, 0x0da24260, v193
	v_mul_f32_e32 v250, v250, v192
	v_mul_f32_e32 v251, v251, v193
	v_mul_f32_e32 v126, v126, v250
	v_mul_f32_e32 v127, v127, v251
	v_lshlrev_b32_e32 v250, 16, v135
	v_and_b32_e32 v251, 0xffff0000, v135
	v_lshlrev_b32_e32 v192, 16, v131
	v_and_b32_e32 v193, 0xffff0000, v131
	v_max_f32_e32 v250, 0x0da24260, v250
	v_max_f32_e32 v251, 0x0da24260, v251
	v_rcp_f32_e32 v250, v250
	v_rcp_f32_e32 v251, v251
	v_max_f32_e32 v192, 0x0da24260, v192
	v_max_f32_e32 v193, 0x0da24260, v193
	v_mul_f32_e32 v250, v250, v192
	v_mul_f32_e32 v251, v251, v193
	v_mul_f32_e32 v128, v128, v250
	v_mul_f32_e32 v129, v129, v251
	v_lshlrev_b32_e32 v250, 16, v136
	v_and_b32_e32 v251, 0xffff0000, v136
	v_lshlrev_b32_e32 v192, 16, v132
	v_and_b32_e32 v193, 0xffff0000, v132
	v_max_f32_e32 v250, 0x0da24260, v250
	v_max_f32_e32 v251, 0x0da24260, v251
	v_rcp_f32_e32 v250, v250
	v_rcp_f32_e32 v251, v251
	v_max_f32_e32 v192, 0x0da24260, v192
	v_max_f32_e32 v193, 0x0da24260, v193
	v_mul_f32_e32 v250, v250, v192
	v_mul_f32_e32 v251, v251, v193
	v_mul_f32_e32 v122, v122, v250
	v_mul_f32_e32 v123, v123, v251
	v_lshlrev_b32_e32 v250, 16, v137
	v_and_b32_e32 v251, 0xffff0000, v137
	v_lshlrev_b32_e32 v192, 16, v133
	v_and_b32_e32 v193, 0xffff0000, v133
	v_max_f32_e32 v250, 0x0da24260, v250
	v_max_f32_e32 v251, 0x0da24260, v251
	v_rcp_f32_e32 v250, v250
	v_rcp_f32_e32 v251, v251
	v_max_f32_e32 v192, 0x0da24260, v192
	v_max_f32_e32 v193, 0x0da24260, v193
	v_mul_f32_e32 v250, v250, v192
	v_mul_f32_e32 v251, v251, v193
	v_mul_f32_e32 v124, v124, v250
	v_mul_f32_e32 v125, v125, v251
	v_mov_b32_e32 v232, v134
	v_mov_b32_e32 v233, v135
	v_mov_b32_e32 v234, v136
	v_mov_b32_e32 v235, v137
	global_load_dwordx4 v[134:137], v248, s[64:65] offset:256
	global_load_dwordx4 v[130:133], v248, s[64:65] offset:2304
	s_waitcnt vmcnt(16)
	v_lshlrev_b32_e32 v250, 16, v142
	v_and_b32_e32 v251, 0xffff0000, v142
	v_lshlrev_b32_e32 v192, 16, v138
	v_and_b32_e32 v193, 0xffff0000, v138
	v_max_f32_e32 v250, 0x0da24260, v250
	v_max_f32_e32 v251, 0x0da24260, v251
	v_rcp_f32_e32 v250, v250
	v_rcp_f32_e32 v251, v251
	v_max_f32_e32 v192, 0x0da24260, v192
	v_max_f32_e32 v193, 0x0da24260, v193
	v_mul_f32_e32 v250, v250, v192
	v_mul_f32_e32 v251, v251, v193
	v_mul_f32_e32 v114, v114, v250
	v_mul_f32_e32 v115, v115, v251
	v_lshlrev_b32_e32 v250, 16, v143
	v_and_b32_e32 v251, 0xffff0000, v143
	v_lshlrev_b32_e32 v192, 16, v139
	v_and_b32_e32 v193, 0xffff0000, v139
	v_max_f32_e32 v250, 0x0da24260, v250
	v_max_f32_e32 v251, 0x0da24260, v251
	v_rcp_f32_e32 v250, v250
	v_rcp_f32_e32 v251, v251
	v_max_f32_e32 v192, 0x0da24260, v192
	v_max_f32_e32 v193, 0x0da24260, v193
	v_mul_f32_e32 v250, v250, v192
	v_mul_f32_e32 v251, v251, v193
	v_mul_f32_e32 v116, v116, v250
	v_mul_f32_e32 v117, v117, v251
	v_lshlrev_b32_e32 v250, 16, v144
	v_and_b32_e32 v251, 0xffff0000, v144
	v_lshlrev_b32_e32 v192, 16, v140
	v_and_b32_e32 v193, 0xffff0000, v140
	v_max_f32_e32 v250, 0x0da24260, v250
	v_max_f32_e32 v251, 0x0da24260, v251
	v_rcp_f32_e32 v250, v250
	v_rcp_f32_e32 v251, v251
	v_max_f32_e32 v192, 0x0da24260, v192
	v_max_f32_e32 v193, 0x0da24260, v193
	v_mul_f32_e32 v250, v250, v192
	v_mul_f32_e32 v251, v251, v193
	v_mul_f32_e32 v106, v106, v250
	v_mul_f32_e32 v107, v107, v251
	v_lshlrev_b32_e32 v250, 16, v145
	v_and_b32_e32 v251, 0xffff0000, v145
	v_lshlrev_b32_e32 v192, 16, v141
	v_and_b32_e32 v193, 0xffff0000, v141
	v_max_f32_e32 v250, 0x0da24260, v250
	v_max_f32_e32 v251, 0x0da24260, v251
	v_rcp_f32_e32 v250, v250
	v_rcp_f32_e32 v251, v251
	v_max_f32_e32 v192, 0x0da24260, v192
	v_max_f32_e32 v193, 0x0da24260, v193
	v_mul_f32_e32 v250, v250, v192
	v_mul_f32_e32 v251, v251, v193
	v_mul_f32_e32 v108, v108, v250
	v_mul_f32_e32 v109, v109, v251
	v_mov_b32_e32 v236, v142
	v_mov_b32_e32 v237, v143
	v_mov_b32_e32 v238, v144
	v_mov_b32_e32 v239, v145
	global_load_dwordx4 v[142:145], v248, s[66:67]
	global_load_dwordx4 v[138:141], v248, s[66:67] offset:2048
	s_waitcnt vmcnt(16)
	v_lshlrev_b32_e32 v250, 16, v150
	v_and_b32_e32 v251, 0xffff0000, v150
	v_lshlrev_b32_e32 v192, 16, v146
	v_and_b32_e32 v193, 0xffff0000, v146
	v_max_f32_e32 v250, 0x0da24260, v250
	v_max_f32_e32 v251, 0x0da24260, v251
	v_rcp_f32_e32 v250, v250
	v_rcp_f32_e32 v251, v251
	v_max_f32_e32 v192, 0x0da24260, v192
	v_max_f32_e32 v193, 0x0da24260, v193
	v_mul_f32_e32 v250, v250, v192
	v_mul_f32_e32 v251, v251, v193
	v_mul_f32_e32 v118, v118, v250
	v_mul_f32_e32 v119, v119, v251
	v_lshlrev_b32_e32 v250, 16, v151
	v_and_b32_e32 v251, 0xffff0000, v151
	v_lshlrev_b32_e32 v192, 16, v147
	v_and_b32_e32 v193, 0xffff0000, v147
	v_max_f32_e32 v250, 0x0da24260, v250
	v_max_f32_e32 v251, 0x0da24260, v251
	v_rcp_f32_e32 v250, v250
	v_rcp_f32_e32 v251, v251
	v_max_f32_e32 v192, 0x0da24260, v192
	v_max_f32_e32 v193, 0x0da24260, v193
	v_mul_f32_e32 v250, v250, v192
	v_mul_f32_e32 v251, v251, v193
	v_mul_f32_e32 v120, v120, v250
	v_mul_f32_e32 v121, v121, v251
	v_lshlrev_b32_e32 v250, 16, v152
	v_and_b32_e32 v251, 0xffff0000, v152
	v_lshlrev_b32_e32 v192, 16, v148
	v_and_b32_e32 v193, 0xffff0000, v148
	v_max_f32_e32 v250, 0x0da24260, v250
	v_max_f32_e32 v251, 0x0da24260, v251
	v_rcp_f32_e32 v250, v250
	v_rcp_f32_e32 v251, v251
	v_max_f32_e32 v192, 0x0da24260, v192
	v_max_f32_e32 v193, 0x0da24260, v193
	v_mul_f32_e32 v250, v250, v192
	v_mul_f32_e32 v251, v251, v193
	v_mul_f32_e32 v110, v110, v250
	v_mul_f32_e32 v111, v111, v251
	v_lshlrev_b32_e32 v250, 16, v153
	v_and_b32_e32 v251, 0xffff0000, v153
	v_lshlrev_b32_e32 v192, 16, v149
	v_and_b32_e32 v193, 0xffff0000, v149
	v_max_f32_e32 v250, 0x0da24260, v250
	v_max_f32_e32 v251, 0x0da24260, v251
	v_rcp_f32_e32 v250, v250
	v_rcp_f32_e32 v251, v251
	v_max_f32_e32 v192, 0x0da24260, v192
	v_max_f32_e32 v193, 0x0da24260, v193
	v_mul_f32_e32 v250, v250, v192
	v_mul_f32_e32 v251, v251, v193
	v_mul_f32_e32 v112, v112, v250
	v_mul_f32_e32 v113, v113, v251
	v_mov_b32_e32 v240, v150
	v_mov_b32_e32 v241, v151
	v_mov_b32_e32 v242, v152
	v_mov_b32_e32 v243, v153
	global_load_dwordx4 v[150:153], v248, s[66:67] offset:256
	global_load_dwordx4 v[146:149], v248, s[66:67] offset:2304
	s_waitcnt vmcnt(16)
	v_lshlrev_b32_e32 v250, 16, v168
	v_and_b32_e32 v251, 0xffff0000, v168
	v_lshlrev_b32_e32 v192, 16, v164
	v_and_b32_e32 v193, 0xffff0000, v164
	v_max_f32_e32 v250, 0x0da24260, v250
	v_max_f32_e32 v251, 0x0da24260, v251
	v_rcp_f32_e32 v250, v250
	v_rcp_f32_e32 v251, v251
	v_max_f32_e32 v192, 0x0da24260, v192
	v_max_f32_e32 v193, 0x0da24260, v193
	v_mul_f32_e32 v250, v250, v192
	v_mul_f32_e32 v251, v251, v193
	v_mul_f32_e32 v102, v102, v250
	v_mul_f32_e32 v103, v103, v251
	v_lshlrev_b32_e32 v250, 16, v169
	v_and_b32_e32 v251, 0xffff0000, v169
	v_lshlrev_b32_e32 v192, 16, v165
	v_and_b32_e32 v193, 0xffff0000, v165
	v_max_f32_e32 v250, 0x0da24260, v250
	v_max_f32_e32 v251, 0x0da24260, v251
	v_rcp_f32_e32 v250, v250
	v_rcp_f32_e32 v251, v251
	v_max_f32_e32 v192, 0x0da24260, v192
	v_max_f32_e32 v193, 0x0da24260, v193
	v_mul_f32_e32 v250, v250, v192
	v_mul_f32_e32 v251, v251, v193
	v_mul_f32_e32 v104, v104, v250
	v_mul_f32_e32 v105, v105, v251
	v_lshlrev_b32_e32 v250, 16, v170
	v_and_b32_e32 v251, 0xffff0000, v170
	v_lshlrev_b32_e32 v192, 16, v166
	v_and_b32_e32 v193, 0xffff0000, v166
	v_max_f32_e32 v250, 0x0da24260, v250
	v_max_f32_e32 v251, 0x0da24260, v251
	v_rcp_f32_e32 v250, v250
	v_rcp_f32_e32 v251, v251
	v_max_f32_e32 v192, 0x0da24260, v192
	v_max_f32_e32 v193, 0x0da24260, v193
	v_mul_f32_e32 v250, v250, v192
	v_mul_f32_e32 v251, v251, v193
	v_mul_f32_e32 v98, v98, v250
	v_mul_f32_e32 v99, v99, v251
	v_lshlrev_b32_e32 v250, 16, v171
	v_and_b32_e32 v251, 0xffff0000, v171
	v_lshlrev_b32_e32 v192, 16, v167
	v_and_b32_e32 v193, 0xffff0000, v167
	v_max_f32_e32 v250, 0x0da24260, v250
	v_max_f32_e32 v251, 0x0da24260, v251
	v_rcp_f32_e32 v250, v250
	v_rcp_f32_e32 v251, v251
	v_max_f32_e32 v192, 0x0da24260, v192
	v_max_f32_e32 v193, 0x0da24260, v193
	v_mul_f32_e32 v250, v250, v192
	v_mul_f32_e32 v251, v251, v193
	v_mul_f32_e32 v100, v100, v250
	v_mul_f32_e32 v101, v101, v251
	v_mov_b32_e32 v244, v168
	v_mov_b32_e32 v245, v169
	v_mov_b32_e32 v246, v170
	v_mov_b32_e32 v247, v171
	global_load_dwordx4 v[168:171], v248, s[68:69]
	global_load_dwordx4 v[164:167], v248, s[68:69] offset:2048
	s_waitcnt vmcnt(16)
	v_lshlrev_b32_e32 v250, 16, v180
	v_and_b32_e32 v251, 0xffff0000, v180
	v_lshlrev_b32_e32 v192, 16, v172
	v_and_b32_e32 v193, 0xffff0000, v172
	v_max_f32_e32 v250, 0x0da24260, v250
	v_max_f32_e32 v251, 0x0da24260, v251
	v_rcp_f32_e32 v250, v250
	v_rcp_f32_e32 v251, v251
	v_max_f32_e32 v192, 0x0da24260, v192
	v_max_f32_e32 v193, 0x0da24260, v193
	v_mul_f32_e32 v250, v250, v192
	v_mul_f32_e32 v251, v251, v193
	v_mul_f32_e32 v94, v94, v250
	v_mul_f32_e32 v95, v95, v251
	v_lshlrev_b32_e32 v250, 16, v181
	v_and_b32_e32 v251, 0xffff0000, v181
	v_lshlrev_b32_e32 v192, 16, v173
	v_and_b32_e32 v193, 0xffff0000, v173
	v_max_f32_e32 v250, 0x0da24260, v250
	v_max_f32_e32 v251, 0x0da24260, v251
	v_rcp_f32_e32 v250, v250
	v_rcp_f32_e32 v251, v251
	v_max_f32_e32 v192, 0x0da24260, v192
	v_max_f32_e32 v193, 0x0da24260, v193
	v_mul_f32_e32 v250, v250, v192
	v_mul_f32_e32 v251, v251, v193
	v_mul_f32_e32 v96, v96, v250
	v_mul_f32_e32 v97, v97, v251
	v_lshlrev_b32_e32 v250, 16, v182
	v_and_b32_e32 v251, 0xffff0000, v182
	v_lshlrev_b32_e32 v192, 16, v174
	v_and_b32_e32 v193, 0xffff0000, v174
	v_max_f32_e32 v250, 0x0da24260, v250
	v_max_f32_e32 v251, 0x0da24260, v251
	v_rcp_f32_e32 v250, v250
	v_rcp_f32_e32 v251, v251
	v_max_f32_e32 v192, 0x0da24260, v192
	v_max_f32_e32 v193, 0x0da24260, v193
	v_mul_f32_e32 v250, v250, v192
	v_mul_f32_e32 v251, v251, v193
	v_mul_f32_e32 v90, v90, v250
	v_mul_f32_e32 v91, v91, v251
	v_lshlrev_b32_e32 v250, 16, v183
	v_and_b32_e32 v251, 0xffff0000, v183
	v_lshlrev_b32_e32 v192, 16, v175
	v_and_b32_e32 v193, 0xffff0000, v175
	v_max_f32_e32 v250, 0x0da24260, v250
	v_max_f32_e32 v251, 0x0da24260, v251
	v_rcp_f32_e32 v250, v250
	v_rcp_f32_e32 v251, v251
	v_max_f32_e32 v192, 0x0da24260, v192
	v_max_f32_e32 v193, 0x0da24260, v193
	v_mul_f32_e32 v250, v250, v192
	v_mul_f32_e32 v251, v251, v193
	v_mul_f32_e32 v92, v92, v250
	v_mul_f32_e32 v93, v93, v251
	global_load_dwordx4 v[180:183], v248, s[68:69] offset:256
	global_load_dwordx4 v[172:175], v248, s[68:69] offset:2304
	s_waitcnt vmcnt(16)
	v_lshlrev_b32_e32 v250, 16, v188
	v_and_b32_e32 v251, 0xffff0000, v188
	v_lshlrev_b32_e32 v192, 16, v184
	v_and_b32_e32 v193, 0xffff0000, v184
	v_max_f32_e32 v250, 0x0da24260, v250
	v_max_f32_e32 v251, 0x0da24260, v251
	v_rcp_f32_e32 v250, v250
	v_rcp_f32_e32 v251, v251
	v_max_f32_e32 v192, 0x0da24260, v192
	v_max_f32_e32 v193, 0x0da24260, v193
	v_mul_f32_e32 v250, v250, v192
	v_mul_f32_e32 v251, v251, v193
	v_mul_f32_e32 v82, v82, v250
	v_mul_f32_e32 v83, v83, v251
	v_lshlrev_b32_e32 v250, 16, v189
	v_and_b32_e32 v251, 0xffff0000, v189
	v_lshlrev_b32_e32 v192, 16, v185
	v_and_b32_e32 v193, 0xffff0000, v185
	v_max_f32_e32 v250, 0x0da24260, v250
	v_max_f32_e32 v251, 0x0da24260, v251
	v_rcp_f32_e32 v250, v250
	v_rcp_f32_e32 v251, v251
	v_max_f32_e32 v192, 0x0da24260, v192
	v_max_f32_e32 v193, 0x0da24260, v193
	v_mul_f32_e32 v250, v250, v192
	v_mul_f32_e32 v251, v251, v193
	v_mul_f32_e32 v84, v84, v250
	v_mul_f32_e32 v85, v85, v251
	v_lshlrev_b32_e32 v250, 16, v190
	v_and_b32_e32 v251, 0xffff0000, v190
	v_lshlrev_b32_e32 v192, 16, v186
	v_and_b32_e32 v193, 0xffff0000, v186
	v_max_f32_e32 v250, 0x0da24260, v250
	v_max_f32_e32 v251, 0x0da24260, v251
	v_rcp_f32_e32 v250, v250
	v_rcp_f32_e32 v251, v251
	v_max_f32_e32 v192, 0x0da24260, v192
	v_max_f32_e32 v193, 0x0da24260, v193
	v_mul_f32_e32 v250, v250, v192
	v_mul_f32_e32 v251, v251, v193
	v_mul_f32_e32 v74, v74, v250
	v_mul_f32_e32 v75, v75, v251
	v_lshlrev_b32_e32 v250, 16, v191
	v_and_b32_e32 v251, 0xffff0000, v191
	v_lshlrev_b32_e32 v192, 16, v187
	v_and_b32_e32 v193, 0xffff0000, v187
	v_max_f32_e32 v250, 0x0da24260, v250
	v_max_f32_e32 v251, 0x0da24260, v251
	v_rcp_f32_e32 v250, v250
	v_rcp_f32_e32 v251, v251
	v_max_f32_e32 v192, 0x0da24260, v192
	v_max_f32_e32 v193, 0x0da24260, v193
	v_mul_f32_e32 v250, v250, v192
	v_mul_f32_e32 v251, v251, v193
	v_mul_f32_e32 v76, v76, v250
	v_mul_f32_e32 v77, v77, v251
	global_load_dwordx4 v[188:191], v248, s[70:71]
	global_load_dwordx4 v[184:187], v248, s[70:71] offset:2048
	s_waitcnt vmcnt(16)
	v_lshlrev_b32_e32 v250, 16, v212
	v_and_b32_e32 v251, 0xffff0000, v212
	v_lshlrev_b32_e32 v192, 16, v198
	v_and_b32_e32 v193, 0xffff0000, v198
	v_max_f32_e32 v250, 0x0da24260, v250
	v_max_f32_e32 v251, 0x0da24260, v251
	v_rcp_f32_e32 v250, v250
	v_rcp_f32_e32 v251, v251
	v_max_f32_e32 v192, 0x0da24260, v192
	v_max_f32_e32 v193, 0x0da24260, v193
	v_mul_f32_e32 v250, v250, v192
	v_mul_f32_e32 v251, v251, v193
	v_mul_f32_e32 v86, v86, v250
	v_mul_f32_e32 v87, v87, v251
	v_lshlrev_b32_e32 v250, 16, v213
	v_and_b32_e32 v251, 0xffff0000, v213
	v_lshlrev_b32_e32 v192, 16, v199
	v_and_b32_e32 v193, 0xffff0000, v199
	v_max_f32_e32 v250, 0x0da24260, v250
	v_max_f32_e32 v251, 0x0da24260, v251
	v_rcp_f32_e32 v250, v250
	v_rcp_f32_e32 v251, v251
	v_max_f32_e32 v192, 0x0da24260, v192
	v_max_f32_e32 v193, 0x0da24260, v193
	v_mul_f32_e32 v250, v250, v192
	v_mul_f32_e32 v251, v251, v193
	v_mul_f32_e32 v88, v88, v250
	v_mul_f32_e32 v89, v89, v251
	v_lshlrev_b32_e32 v250, 16, v214
	v_and_b32_e32 v251, 0xffff0000, v214
	v_lshlrev_b32_e32 v192, 16, v200
	v_and_b32_e32 v193, 0xffff0000, v200
	v_max_f32_e32 v250, 0x0da24260, v250
	v_max_f32_e32 v251, 0x0da24260, v251
	v_rcp_f32_e32 v250, v250
	v_rcp_f32_e32 v251, v251
	v_max_f32_e32 v192, 0x0da24260, v192
	v_max_f32_e32 v193, 0x0da24260, v193
	v_mul_f32_e32 v250, v250, v192
	v_mul_f32_e32 v251, v251, v193
	v_mul_f32_e32 v78, v78, v250
	v_mul_f32_e32 v79, v79, v251
	v_lshlrev_b32_e32 v250, 16, v215
	v_and_b32_e32 v251, 0xffff0000, v215
	v_lshlrev_b32_e32 v192, 16, v201
	v_and_b32_e32 v193, 0xffff0000, v201
	v_max_f32_e32 v250, 0x0da24260, v250
	v_max_f32_e32 v251, 0x0da24260, v251
	v_rcp_f32_e32 v250, v250
	v_rcp_f32_e32 v251, v251
	v_max_f32_e32 v192, 0x0da24260, v192
	v_max_f32_e32 v193, 0x0da24260, v193
	v_mul_f32_e32 v250, v250, v192
	v_mul_f32_e32 v251, v251, v193
	v_mul_f32_e32 v80, v80, v250
	v_mul_f32_e32 v81, v81, v251
	global_load_dwordx4 v[212:215], v248, s[70:71] offset:256
	global_load_dwordx4 v[198:201], v248, s[70:71] offset:2304
	s_waitcnt vmcnt(16)
	v_lshlrev_b32_e32 v250, 16, v220
	v_and_b32_e32 v251, 0xffff0000, v220
	v_lshlrev_b32_e32 v192, 16, v216
	v_and_b32_e32 v193, 0xffff0000, v216
	v_max_f32_e32 v250, 0x0da24260, v250
	v_max_f32_e32 v251, 0x0da24260, v251
	v_rcp_f32_e32 v250, v250
	v_rcp_f32_e32 v251, v251
	v_max_f32_e32 v192, 0x0da24260, v192
	v_max_f32_e32 v193, 0x0da24260, v193
	v_mul_f32_e32 v250, v250, v192
	v_mul_f32_e32 v251, v251, v193
	v_mul_f32_e32 v70, v70, v250
	v_mul_f32_e32 v71, v71, v251
	v_lshlrev_b32_e32 v250, 16, v221
	v_and_b32_e32 v251, 0xffff0000, v221
	v_lshlrev_b32_e32 v192, 16, v217
	v_and_b32_e32 v193, 0xffff0000, v217
	v_max_f32_e32 v250, 0x0da24260, v250
	v_max_f32_e32 v251, 0x0da24260, v251
	v_rcp_f32_e32 v250, v250
	v_rcp_f32_e32 v251, v251
	v_max_f32_e32 v192, 0x0da24260, v192
	v_max_f32_e32 v193, 0x0da24260, v193
	v_mul_f32_e32 v250, v250, v192
	v_mul_f32_e32 v251, v251, v193
	v_mul_f32_e32 v72, v72, v250
	v_mul_f32_e32 v73, v73, v251
	v_lshlrev_b32_e32 v250, 16, v222
	v_and_b32_e32 v251, 0xffff0000, v222
	v_lshlrev_b32_e32 v192, 16, v218
	v_and_b32_e32 v193, 0xffff0000, v218
	v_max_f32_e32 v250, 0x0da24260, v250
	v_max_f32_e32 v251, 0x0da24260, v251
	v_rcp_f32_e32 v250, v250
	v_rcp_f32_e32 v251, v251
	v_max_f32_e32 v192, 0x0da24260, v192
	v_max_f32_e32 v193, 0x0da24260, v193
	v_mul_f32_e32 v250, v250, v192
	v_mul_f32_e32 v251, v251, v193
	v_mul_f32_e32 v66, v66, v250
	v_mul_f32_e32 v67, v67, v251
	v_lshlrev_b32_e32 v250, 16, v223
	v_and_b32_e32 v251, 0xffff0000, v223
	v_lshlrev_b32_e32 v192, 16, v219
	v_and_b32_e32 v193, 0xffff0000, v219
	v_max_f32_e32 v250, 0x0da24260, v250
	v_max_f32_e32 v251, 0x0da24260, v251
	v_rcp_f32_e32 v250, v250
	v_rcp_f32_e32 v251, v251
	v_max_f32_e32 v192, 0x0da24260, v192
	v_max_f32_e32 v193, 0x0da24260, v193
	v_mul_f32_e32 v250, v250, v192
	v_mul_f32_e32 v251, v251, v193
	v_mul_f32_e32 v68, v68, v250
	v_mul_f32_e32 v69, v69, v251
	s_waitcnt vmcnt(14)
	v_lshlrev_b32_e32 v250, 16, v228
	v_and_b32_e32 v251, 0xffff0000, v228
	v_lshlrev_b32_e32 v192, 16, v224
	v_and_b32_e32 v193, 0xffff0000, v224
	v_max_f32_e32 v250, 0x0da24260, v250
	v_max_f32_e32 v251, 0x0da24260, v251
	v_rcp_f32_e32 v250, v250
	v_rcp_f32_e32 v251, v251
	v_max_f32_e32 v192, 0x0da24260, v192
	v_max_f32_e32 v193, 0x0da24260, v193
	v_mul_f32_e32 v250, v250, v192
	v_mul_f32_e32 v251, v251, v193
	v_mul_f32_e32 v62, v62, v250
	v_mul_f32_e32 v63, v63, v251
	v_lshlrev_b32_e32 v250, 16, v229
	v_and_b32_e32 v251, 0xffff0000, v229
	v_lshlrev_b32_e32 v192, 16, v225
	v_and_b32_e32 v193, 0xffff0000, v225
	v_max_f32_e32 v250, 0x0da24260, v250
	v_max_f32_e32 v251, 0x0da24260, v251
	v_rcp_f32_e32 v250, v250
	v_rcp_f32_e32 v251, v251
	v_max_f32_e32 v192, 0x0da24260, v192
	v_max_f32_e32 v193, 0x0da24260, v193
	v_mul_f32_e32 v250, v250, v192
	v_mul_f32_e32 v251, v251, v193
	v_mul_f32_e32 v64, v64, v250
	v_mul_f32_e32 v65, v65, v251
	v_lshlrev_b32_e32 v250, 16, v230
	v_and_b32_e32 v251, 0xffff0000, v230
	v_lshlrev_b32_e32 v192, 16, v226
	v_and_b32_e32 v193, 0xffff0000, v226
	v_max_f32_e32 v250, 0x0da24260, v250
	v_max_f32_e32 v251, 0x0da24260, v251
	v_rcp_f32_e32 v250, v250
	v_rcp_f32_e32 v251, v251
	v_max_f32_e32 v192, 0x0da24260, v192
	v_max_f32_e32 v193, 0x0da24260, v193
	v_mul_f32_e32 v250, v250, v192
	v_mul_f32_e32 v251, v251, v193
	v_mul_f32_e32 v58, v58, v250
	v_mul_f32_e32 v59, v59, v251
	v_lshlrev_b32_e32 v250, 16, v231
	v_and_b32_e32 v251, 0xffff0000, v231
	v_lshlrev_b32_e32 v192, 16, v227
	v_and_b32_e32 v193, 0xffff0000, v227
	v_max_f32_e32 v250, 0x0da24260, v250
	v_max_f32_e32 v251, 0x0da24260, v251
	v_rcp_f32_e32 v250, v250
	v_rcp_f32_e32 v251, v251
	v_max_f32_e32 v192, 0x0da24260, v192
	v_max_f32_e32 v193, 0x0da24260, v193
	v_mul_f32_e32 v250, v250, v192
	v_mul_f32_e32 v251, v251, v193
	v_mul_f32_e32 v60, v60, v250
	v_mul_f32_e32 v61, v61, v251
	s_waitcnt vmcnt(12)
	v_lshlrev_b32_e32 v250, 16, v130
	v_and_b32_e32 v251, 0xffff0000, v130
	v_lshlrev_b32_e32 v192, 16, v134
	v_and_b32_e32 v193, 0xffff0000, v134
	v_max_f32_e32 v250, 0x0da24260, v250
	v_max_f32_e32 v251, 0x0da24260, v251
	v_rcp_f32_e32 v250, v250
	v_rcp_f32_e32 v251, v251
	v_max_f32_e32 v192, 0x0da24260, v192
	v_max_f32_e32 v193, 0x0da24260, v193
	v_mul_f32_e32 v250, v250, v192
	v_mul_f32_e32 v251, v251, v193
	v_mul_f32_e32 v50, v50, v250
	v_mul_f32_e32 v51, v51, v251
	v_lshlrev_b32_e32 v250, 16, v131
	v_and_b32_e32 v251, 0xffff0000, v131
	v_lshlrev_b32_e32 v192, 16, v135
	v_and_b32_e32 v193, 0xffff0000, v135
	v_max_f32_e32 v250, 0x0da24260, v250
	v_max_f32_e32 v251, 0x0da24260, v251
	v_rcp_f32_e32 v250, v250
	v_rcp_f32_e32 v251, v251
	v_max_f32_e32 v192, 0x0da24260, v192
	v_max_f32_e32 v193, 0x0da24260, v193
	v_mul_f32_e32 v250, v250, v192
	v_mul_f32_e32 v251, v251, v193
	v_mul_f32_e32 v52, v52, v250
	v_mul_f32_e32 v53, v53, v251
	v_lshlrev_b32_e32 v250, 16, v132
	v_and_b32_e32 v251, 0xffff0000, v132
	v_lshlrev_b32_e32 v192, 16, v136
	v_and_b32_e32 v193, 0xffff0000, v136
	v_max_f32_e32 v250, 0x0da24260, v250
	v_max_f32_e32 v251, 0x0da24260, v251
	v_rcp_f32_e32 v250, v250
	v_rcp_f32_e32 v251, v251
	v_max_f32_e32 v192, 0x0da24260, v192
	v_max_f32_e32 v193, 0x0da24260, v193
	v_mul_f32_e32 v250, v250, v192
	v_mul_f32_e32 v251, v251, v193
	v_mul_f32_e32 v42, v42, v250
	v_mul_f32_e32 v43, v43, v251
	v_lshlrev_b32_e32 v250, 16, v133
	v_and_b32_e32 v251, 0xffff0000, v133
	v_lshlrev_b32_e32 v192, 16, v137
	v_and_b32_e32 v193, 0xffff0000, v137
	v_max_f32_e32 v250, 0x0da24260, v250
	v_max_f32_e32 v251, 0x0da24260, v251
	v_rcp_f32_e32 v250, v250
	v_rcp_f32_e32 v251, v251
	v_max_f32_e32 v192, 0x0da24260, v192
	v_max_f32_e32 v193, 0x0da24260, v193
	v_mul_f32_e32 v250, v250, v192
	v_mul_f32_e32 v251, v251, v193
	v_mul_f32_e32 v44, v44, v250
	v_mul_f32_e32 v45, v45, v251
	s_waitcnt vmcnt(10)
	v_lshlrev_b32_e32 v250, 16, v138
	v_and_b32_e32 v251, 0xffff0000, v138
	v_lshlrev_b32_e32 v192, 16, v142
	v_and_b32_e32 v193, 0xffff0000, v142
	v_max_f32_e32 v250, 0x0da24260, v250
	v_max_f32_e32 v251, 0x0da24260, v251
	v_rcp_f32_e32 v250, v250
	v_rcp_f32_e32 v251, v251
	v_max_f32_e32 v192, 0x0da24260, v192
	v_max_f32_e32 v193, 0x0da24260, v193
	v_mul_f32_e32 v250, v250, v192
	v_mul_f32_e32 v251, v251, v193
	v_mul_f32_e32 v54, v54, v250
	v_mul_f32_e32 v55, v55, v251
	v_lshlrev_b32_e32 v250, 16, v139
	v_and_b32_e32 v251, 0xffff0000, v139
	v_lshlrev_b32_e32 v192, 16, v143
	v_and_b32_e32 v193, 0xffff0000, v143
	v_max_f32_e32 v250, 0x0da24260, v250
	v_max_f32_e32 v251, 0x0da24260, v251
	v_rcp_f32_e32 v250, v250
	v_rcp_f32_e32 v251, v251
	v_max_f32_e32 v192, 0x0da24260, v192
	v_max_f32_e32 v193, 0x0da24260, v193
	v_mul_f32_e32 v250, v250, v192
	v_mul_f32_e32 v251, v251, v193
	v_mul_f32_e32 v56, v56, v250
	v_mul_f32_e32 v57, v57, v251
	v_lshlrev_b32_e32 v250, 16, v140
	v_and_b32_e32 v251, 0xffff0000, v140
	v_lshlrev_b32_e32 v192, 16, v144
	v_and_b32_e32 v193, 0xffff0000, v144
	v_max_f32_e32 v250, 0x0da24260, v250
	v_max_f32_e32 v251, 0x0da24260, v251
	v_rcp_f32_e32 v250, v250
	v_rcp_f32_e32 v251, v251
	v_max_f32_e32 v192, 0x0da24260, v192
	v_max_f32_e32 v193, 0x0da24260, v193
	v_mul_f32_e32 v250, v250, v192
	v_mul_f32_e32 v251, v251, v193
	v_mul_f32_e32 v46, v46, v250
	v_mul_f32_e32 v47, v47, v251
	v_lshlrev_b32_e32 v250, 16, v141
	v_and_b32_e32 v251, 0xffff0000, v141
	v_lshlrev_b32_e32 v192, 16, v145
	v_and_b32_e32 v193, 0xffff0000, v145
	v_max_f32_e32 v250, 0x0da24260, v250
	v_max_f32_e32 v251, 0x0da24260, v251
	v_rcp_f32_e32 v250, v250
	v_rcp_f32_e32 v251, v251
	v_max_f32_e32 v192, 0x0da24260, v192
	v_max_f32_e32 v193, 0x0da24260, v193
	v_mul_f32_e32 v250, v250, v192
	v_mul_f32_e32 v251, v251, v193
	v_mul_f32_e32 v48, v48, v250
	v_mul_f32_e32 v49, v49, v251
	s_waitcnt vmcnt(8)
	v_lshlrev_b32_e32 v250, 16, v146
	v_and_b32_e32 v251, 0xffff0000, v146
	v_lshlrev_b32_e32 v192, 16, v150
	v_and_b32_e32 v193, 0xffff0000, v150
	v_max_f32_e32 v250, 0x0da24260, v250
	v_max_f32_e32 v251, 0x0da24260, v251
	v_rcp_f32_e32 v250, v250
	v_rcp_f32_e32 v251, v251
	v_max_f32_e32 v192, 0x0da24260, v192
	v_max_f32_e32 v193, 0x0da24260, v193
	v_mul_f32_e32 v250, v250, v192
	v_mul_f32_e32 v251, v251, v193
	v_mul_f32_e32 v38, v38, v250
	v_mul_f32_e32 v39, v39, v251
	v_lshlrev_b32_e32 v250, 16, v147
	v_and_b32_e32 v251, 0xffff0000, v147
	v_lshlrev_b32_e32 v192, 16, v151
	v_and_b32_e32 v193, 0xffff0000, v151
	v_max_f32_e32 v250, 0x0da24260, v250
	v_max_f32_e32 v251, 0x0da24260, v251
	v_rcp_f32_e32 v250, v250
	v_rcp_f32_e32 v251, v251
	v_max_f32_e32 v192, 0x0da24260, v192
	v_max_f32_e32 v193, 0x0da24260, v193
	v_mul_f32_e32 v250, v250, v192
	v_mul_f32_e32 v251, v251, v193
	v_mul_f32_e32 v40, v40, v250
	v_mul_f32_e32 v41, v41, v251
	v_lshlrev_b32_e32 v250, 16, v148
	v_and_b32_e32 v251, 0xffff0000, v148
	v_lshlrev_b32_e32 v192, 16, v152
	v_and_b32_e32 v193, 0xffff0000, v152
	v_max_f32_e32 v250, 0x0da24260, v250
	v_max_f32_e32 v251, 0x0da24260, v251
	v_rcp_f32_e32 v250, v250
	v_rcp_f32_e32 v251, v251
	v_max_f32_e32 v192, 0x0da24260, v192
	v_max_f32_e32 v193, 0x0da24260, v193
	v_mul_f32_e32 v250, v250, v192
	v_mul_f32_e32 v251, v251, v193
	v_mul_f32_e32 v34, v34, v250
	v_mul_f32_e32 v35, v35, v251
	v_lshlrev_b32_e32 v250, 16, v149
	v_and_b32_e32 v251, 0xffff0000, v149
	v_lshlrev_b32_e32 v192, 16, v153
	v_and_b32_e32 v193, 0xffff0000, v153
	v_max_f32_e32 v250, 0x0da24260, v250
	v_max_f32_e32 v251, 0x0da24260, v251
	v_rcp_f32_e32 v250, v250
	v_rcp_f32_e32 v251, v251
	v_max_f32_e32 v192, 0x0da24260, v192
	v_max_f32_e32 v193, 0x0da24260, v193
	v_mul_f32_e32 v250, v250, v192
	v_mul_f32_e32 v251, v251, v193
	v_mul_f32_e32 v36, v36, v250
	v_mul_f32_e32 v37, v37, v251
	s_waitcnt vmcnt(6)
	v_lshlrev_b32_e32 v250, 16, v164
	v_and_b32_e32 v251, 0xffff0000, v164
	v_lshlrev_b32_e32 v192, 16, v168
	v_and_b32_e32 v193, 0xffff0000, v168
	v_max_f32_e32 v250, 0x0da24260, v250
	v_max_f32_e32 v251, 0x0da24260, v251
	v_rcp_f32_e32 v250, v250
	v_rcp_f32_e32 v251, v251
	v_max_f32_e32 v192, 0x0da24260, v192
	v_max_f32_e32 v193, 0x0da24260, v193
	v_mul_f32_e32 v250, v250, v192
	v_mul_f32_e32 v251, v251, v193
	v_mul_f32_e32 v30, v30, v250
	v_mul_f32_e32 v31, v31, v251
	v_lshlrev_b32_e32 v250, 16, v165
	v_and_b32_e32 v251, 0xffff0000, v165
	v_lshlrev_b32_e32 v192, 16, v169
	v_and_b32_e32 v193, 0xffff0000, v169
	v_max_f32_e32 v250, 0x0da24260, v250
	v_max_f32_e32 v251, 0x0da24260, v251
	v_rcp_f32_e32 v250, v250
	v_rcp_f32_e32 v251, v251
	v_max_f32_e32 v192, 0x0da24260, v192
	v_max_f32_e32 v193, 0x0da24260, v193
	v_mul_f32_e32 v250, v250, v192
	v_mul_f32_e32 v251, v251, v193
	v_mul_f32_e32 v32, v32, v250
	v_mul_f32_e32 v33, v33, v251
	v_lshlrev_b32_e32 v250, 16, v166
	v_and_b32_e32 v251, 0xffff0000, v166
	v_lshlrev_b32_e32 v192, 16, v170
	v_and_b32_e32 v193, 0xffff0000, v170
	v_max_f32_e32 v250, 0x0da24260, v250
	v_max_f32_e32 v251, 0x0da24260, v251
	v_rcp_f32_e32 v250, v250
	v_rcp_f32_e32 v251, v251
	v_max_f32_e32 v192, 0x0da24260, v192
	v_max_f32_e32 v193, 0x0da24260, v193
	v_mul_f32_e32 v250, v250, v192
	v_mul_f32_e32 v251, v251, v193
	v_mul_f32_e32 v26, v26, v250
	v_mul_f32_e32 v27, v27, v251
	v_lshlrev_b32_e32 v250, 16, v167
	v_and_b32_e32 v251, 0xffff0000, v167
	v_lshlrev_b32_e32 v192, 16, v171
	v_and_b32_e32 v193, 0xffff0000, v171
	v_max_f32_e32 v250, 0x0da24260, v250
	v_max_f32_e32 v251, 0x0da24260, v251
	v_rcp_f32_e32 v250, v250
	v_rcp_f32_e32 v251, v251
	v_max_f32_e32 v192, 0x0da24260, v192
	v_max_f32_e32 v193, 0x0da24260, v193
	v_mul_f32_e32 v250, v250, v192
	v_mul_f32_e32 v251, v251, v193
	v_mul_f32_e32 v28, v28, v250
	v_mul_f32_e32 v29, v29, v251
	s_waitcnt vmcnt(4)
	v_lshlrev_b32_e32 v250, 16, v172
	v_and_b32_e32 v251, 0xffff0000, v172
	v_lshlrev_b32_e32 v192, 16, v180
	v_and_b32_e32 v193, 0xffff0000, v180
	v_max_f32_e32 v250, 0x0da24260, v250
	v_max_f32_e32 v251, 0x0da24260, v251
	v_rcp_f32_e32 v250, v250
	v_rcp_f32_e32 v251, v251
	v_max_f32_e32 v192, 0x0da24260, v192
	v_max_f32_e32 v193, 0x0da24260, v193
	v_mul_f32_e32 v250, v250, v192
	v_mul_f32_e32 v251, v251, v193
	v_mul_f32_e32 v18, v18, v250
	v_mul_f32_e32 v19, v19, v251
	v_lshlrev_b32_e32 v250, 16, v173
	v_and_b32_e32 v251, 0xffff0000, v173
	v_lshlrev_b32_e32 v192, 16, v181
	v_and_b32_e32 v193, 0xffff0000, v181
	v_max_f32_e32 v250, 0x0da24260, v250
	v_max_f32_e32 v251, 0x0da24260, v251
	v_rcp_f32_e32 v250, v250
	v_rcp_f32_e32 v251, v251
	v_max_f32_e32 v192, 0x0da24260, v192
	v_max_f32_e32 v193, 0x0da24260, v193
	v_mul_f32_e32 v250, v250, v192
	v_mul_f32_e32 v251, v251, v193
	v_mul_f32_e32 v20, v20, v250
	v_mul_f32_e32 v21, v21, v251
	v_lshlrev_b32_e32 v250, 16, v174
	v_and_b32_e32 v251, 0xffff0000, v174
	v_lshlrev_b32_e32 v192, 16, v182
	v_and_b32_e32 v193, 0xffff0000, v182
	v_max_f32_e32 v250, 0x0da24260, v250
	v_max_f32_e32 v251, 0x0da24260, v251
	v_rcp_f32_e32 v250, v250
	v_rcp_f32_e32 v251, v251
	v_max_f32_e32 v192, 0x0da24260, v192
	v_max_f32_e32 v193, 0x0da24260, v193
	v_mul_f32_e32 v250, v250, v192
	v_mul_f32_e32 v251, v251, v193
	v_mul_f32_e32 v10, v10, v250
	v_mul_f32_e32 v11, v11, v251
	v_lshlrev_b32_e32 v250, 16, v175
	v_and_b32_e32 v251, 0xffff0000, v175
	v_lshlrev_b32_e32 v192, 16, v183
	v_and_b32_e32 v193, 0xffff0000, v183
	v_max_f32_e32 v250, 0x0da24260, v250
	v_max_f32_e32 v251, 0x0da24260, v251
	v_rcp_f32_e32 v250, v250
	v_rcp_f32_e32 v251, v251
	v_max_f32_e32 v192, 0x0da24260, v192
	v_max_f32_e32 v193, 0x0da24260, v193
	v_mul_f32_e32 v250, v250, v192
	v_mul_f32_e32 v251, v251, v193
	v_mul_f32_e32 v12, v12, v250
	v_mul_f32_e32 v13, v13, v251
	s_waitcnt vmcnt(2)
	v_lshlrev_b32_e32 v250, 16, v184
	v_and_b32_e32 v251, 0xffff0000, v184
	v_lshlrev_b32_e32 v192, 16, v188
	v_and_b32_e32 v193, 0xffff0000, v188
	v_max_f32_e32 v250, 0x0da24260, v250
	v_max_f32_e32 v251, 0x0da24260, v251
	v_rcp_f32_e32 v250, v250
	v_rcp_f32_e32 v251, v251
	v_max_f32_e32 v192, 0x0da24260, v192
	v_max_f32_e32 v193, 0x0da24260, v193
	v_mul_f32_e32 v250, v250, v192
	v_mul_f32_e32 v251, v251, v193
	v_mul_f32_e32 v22, v22, v250
	v_mul_f32_e32 v23, v23, v251
	v_lshlrev_b32_e32 v250, 16, v185
	v_and_b32_e32 v251, 0xffff0000, v185
	v_lshlrev_b32_e32 v192, 16, v189
	v_and_b32_e32 v193, 0xffff0000, v189
	v_max_f32_e32 v250, 0x0da24260, v250
	v_max_f32_e32 v251, 0x0da24260, v251
	v_rcp_f32_e32 v250, v250
	v_rcp_f32_e32 v251, v251
	v_max_f32_e32 v192, 0x0da24260, v192
	v_max_f32_e32 v193, 0x0da24260, v193
	v_mul_f32_e32 v250, v250, v192
	v_mul_f32_e32 v251, v251, v193
	v_mul_f32_e32 v24, v24, v250
	v_mul_f32_e32 v25, v25, v251
	v_lshlrev_b32_e32 v250, 16, v186
	v_and_b32_e32 v251, 0xffff0000, v186
	v_lshlrev_b32_e32 v192, 16, v190
	v_and_b32_e32 v193, 0xffff0000, v190
	v_max_f32_e32 v250, 0x0da24260, v250
	v_max_f32_e32 v251, 0x0da24260, v251
	v_rcp_f32_e32 v250, v250
	v_rcp_f32_e32 v251, v251
	v_max_f32_e32 v192, 0x0da24260, v192
	v_max_f32_e32 v193, 0x0da24260, v193
	v_mul_f32_e32 v250, v250, v192
	v_mul_f32_e32 v251, v251, v193
	v_mul_f32_e32 v14, v14, v250
	v_mul_f32_e32 v15, v15, v251
	v_lshlrev_b32_e32 v250, 16, v187
	v_and_b32_e32 v251, 0xffff0000, v187
	v_lshlrev_b32_e32 v192, 16, v191
	v_and_b32_e32 v193, 0xffff0000, v191
	v_max_f32_e32 v250, 0x0da24260, v250
	v_max_f32_e32 v251, 0x0da24260, v251
	v_rcp_f32_e32 v250, v250
	v_rcp_f32_e32 v251, v251
	v_max_f32_e32 v192, 0x0da24260, v192
	v_max_f32_e32 v193, 0x0da24260, v193
	v_mul_f32_e32 v250, v250, v192
	v_mul_f32_e32 v251, v251, v193
	v_mul_f32_e32 v16, v16, v250
	v_mul_f32_e32 v17, v17, v251
	s_waitcnt vmcnt(0)
	v_lshlrev_b32_e32 v250, 16, v198
	v_and_b32_e32 v251, 0xffff0000, v198
	v_lshlrev_b32_e32 v192, 16, v212
	v_and_b32_e32 v193, 0xffff0000, v212
	v_max_f32_e32 v250, 0x0da24260, v250
	v_max_f32_e32 v251, 0x0da24260, v251
	v_rcp_f32_e32 v250, v250
	v_rcp_f32_e32 v251, v251
	v_max_f32_e32 v192, 0x0da24260, v192
	v_max_f32_e32 v193, 0x0da24260, v193
	v_mul_f32_e32 v250, v250, v192
	v_mul_f32_e32 v251, v251, v193
	v_mul_f32_e32 v6, v6, v250
	v_mul_f32_e32 v7, v7, v251
	v_lshlrev_b32_e32 v250, 16, v199
	v_and_b32_e32 v251, 0xffff0000, v199
	v_lshlrev_b32_e32 v192, 16, v213
	v_and_b32_e32 v193, 0xffff0000, v213
	v_max_f32_e32 v250, 0x0da24260, v250
	v_max_f32_e32 v251, 0x0da24260, v251
	v_rcp_f32_e32 v250, v250
	v_rcp_f32_e32 v251, v251
	v_max_f32_e32 v192, 0x0da24260, v192
	v_max_f32_e32 v193, 0x0da24260, v193
	v_mul_f32_e32 v250, v250, v192
	v_mul_f32_e32 v251, v251, v193
	v_mul_f32_e32 v8, v8, v250
	v_mul_f32_e32 v9, v9, v251
	v_lshlrev_b32_e32 v250, 16, v200
	v_and_b32_e32 v251, 0xffff0000, v200
	v_lshlrev_b32_e32 v192, 16, v214
	v_and_b32_e32 v193, 0xffff0000, v214
	v_max_f32_e32 v250, 0x0da24260, v250
	v_max_f32_e32 v251, 0x0da24260, v251
	v_rcp_f32_e32 v250, v250
	v_rcp_f32_e32 v251, v251
	v_max_f32_e32 v192, 0x0da24260, v192
	v_max_f32_e32 v193, 0x0da24260, v193
	v_mul_f32_e32 v250, v250, v192
	v_mul_f32_e32 v251, v251, v193
	v_mul_f32_e32 v2, v2, v250
	v_mul_f32_e32 v3, v3, v251
	v_lshlrev_b32_e32 v250, 16, v201
	v_and_b32_e32 v251, 0xffff0000, v201
	v_lshlrev_b32_e32 v192, 16, v215
	v_and_b32_e32 v193, 0xffff0000, v215
	v_max_f32_e32 v250, 0x0da24260, v250
	v_max_f32_e32 v251, 0x0da24260, v251
	v_rcp_f32_e32 v250, v250
	v_rcp_f32_e32 v251, v251
	v_max_f32_e32 v192, 0x0da24260, v192
	v_max_f32_e32 v193, 0x0da24260, v193
	v_mul_f32_e32 v250, v250, v192
	v_mul_f32_e32 v251, v251, v193
	v_mul_f32_e32 v4, v4, v250
	v_mul_f32_e32 v5, v5, v251
	s_branch .Lm_done
.Lm_mid:
	global_load_dwordx4 v[130:133], v248, s[56:57] offset:2048
	global_load_dwordx4 v[134:137], v248, s[56:57] offset:2304
	global_load_dwordx4 v[138:141], v248, s[58:59] offset:2048
	global_load_dwordx4 v[142:145], v248, s[58:59] offset:2304
	global_load_dwordx4 v[146:149], v248, s[60:61]
	global_load_dwordx4 v[150:153], v248, s[60:61] offset:2048
	global_load_dwordx4 v[164:167], v248, s[60:61] offset:256
	global_load_dwordx4 v[168:171], v248, s[60:61] offset:2304
	global_load_dwordx4 v[172:175], v248, s[62:63]
	global_load_dwordx4 v[180:183], v248, s[62:63] offset:2048
	global_load_dwordx4 v[184:187], v248, s[62:63] offset:256
	global_load_dwordx4 v[188:191], v248, s[62:63] offset:2304
	global_load_dwordx4 v[198:201], v248, s[64:65]
	global_load_dwordx4 v[212:215], v248, s[64:65] offset:2048
	global_load_dwordx4 v[216:219], v248, s[64:65] offset:256
	global_load_dwordx4 v[220:223], v248, s[64:65] offset:2304
	global_load_dwordx4 v[224:227], v248, s[66:67]
	global_load_dwordx4 v[228:231], v248, s[66:67] offset:2048
	s_waitcnt vmcnt(17)
	v_lshlrev_b32_e32 v250, 16, v130
	v_and_b32_e32 v251, 0xffff0000, v130
	v_lshlrev_b32_e32 v192, 16, v232
	v_and_b32_e32 v193, 0xffff0000, v232
	v_max_f32_e32 v250, 0x0da24260, v250
	v_max_f32_e32 v251, 0x0da24260, v251
	v_rcp_f32_e32 v250, v250
	v_rcp_f32_e32 v251, v251
	v_max_f32_e32 v192, 0x0da24260, v192
	v_max_f32_e32 v193, 0x0da24260, v193
	v_mul_f32_e32 v250, v250, v192
	v_mul_f32_e32 v251, v251, v193
	v_mul_f32_e32 v126, v126, v250
	v_mul_f32_e32 v127, v127, v251
	v_lshlrev_b32_e32 v250, 16, v131
	v_and_b32_e32 v251, 0xffff0000, v131
	v_lshlrev_b32_e32 v192, 16, v233
	v_and_b32_e32 v193, 0xffff0000, v233
	v_max_f32_e32 v250, 0x0da24260, v250
	v_max_f32_e32 v251, 0x0da24260, v251
	v_rcp_f32_e32 v250, v250
	v_rcp_f32_e32 v251, v251
	v_max_f32_e32 v192, 0x0da24260, v192
	v_max_f32_e32 v193, 0x0da24260, v193
	v_mul_f32_e32 v250, v250, v192
	v_mul_f32_e32 v251, v251, v193
	v_mul_f32_e32 v128, v128, v250
	v_mul_f32_e32 v129, v129, v251
	v_lshlrev_b32_e32 v250, 16, v132
	v_and_b32_e32 v251, 0xffff0000, v132
	v_lshlrev_b32_e32 v192, 16, v234
	v_and_b32_e32 v193, 0xffff0000, v234
	v_max_f32_e32 v250, 0x0da24260, v250
	v_max_f32_e32 v251, 0x0da24260, v251
	v_rcp_f32_e32 v250, v250
	v_rcp_f32_e32 v251, v251
	v_max_f32_e32 v192, 0x0da24260, v192
	v_max_f32_e32 v193, 0x0da24260, v193
	v_mul_f32_e32 v250, v250, v192
	v_mul_f32_e32 v251, v251, v193
	v_mul_f32_e32 v122, v122, v250
	v_mul_f32_e32 v123, v123, v251
	v_lshlrev_b32_e32 v250, 16, v133
	v_and_b32_e32 v251, 0xffff0000, v133
	v_lshlrev_b32_e32 v192, 16, v235
	v_and_b32_e32 v193, 0xffff0000, v235
	v_max_f32_e32 v250, 0x0da24260, v250
	v_max_f32_e32 v251, 0x0da24260, v251
	v_rcp_f32_e32 v250, v250
	v_rcp_f32_e32 v251, v251
	v_max_f32_e32 v192, 0x0da24260, v192
	v_max_f32_e32 v193, 0x0da24260, v193
	v_mul_f32_e32 v250, v250, v192
	v_mul_f32_e32 v251, v251, v193
	v_mul_f32_e32 v124, v124, v250
	v_mul_f32_e32 v125, v125, v251
	v_mov_b32_e32 v232, v130
	v_mov_b32_e32 v233, v131
	v_mov_b32_e32 v234, v132
	v_mov_b32_e32 v235, v133
	global_load_dwordx4 v[130:133], v248, s[66:67] offset:256
	s_waitcnt vmcnt(17)
	v_lshlrev_b32_e32 v250, 16, v134
	v_and_b32_e32 v251, 0xffff0000, v134
	v_lshlrev_b32_e32 v192, 16, v236
	v_and_b32_e32 v193, 0xffff0000, v236
	v_max_f32_e32 v250, 0x0da24260, v250
	v_max_f32_e32 v251, 0x0da24260, v251
	v_rcp_f32_e32 v250, v250
	v_rcp_f32_e32 v251, v251
	v_max_f32_e32 v192, 0x0da24260, v192
	v_max_f32_e32 v193, 0x0da24260, v193
	v_mul_f32_e32 v250, v250, v192
	v_mul_f32_e32 v251, v251, v193
	v_mul_f32_e32 v114, v114, v250
	v_mul_f32_e32 v115, v115, v251
	v_lshlrev_b32_e32 v250, 16, v135
	v_and_b32_e32 v251, 0xffff0000, v135
	v_lshlrev_b32_e32 v192, 16, v237
	v_and_b32_e32 v193, 0xffff0000, v237
	v_max_f32_e32 v250, 0x0da24260, v250
	v_max_f32_e32 v251, 0x0da24260, v251
	v_rcp_f32_e32 v250, v250
	v_rcp_f32_e32 v251, v251
	v_max_f32_e32 v192, 0x0da24260, v192
	v_max_f32_e32 v193, 0x0da24260, v193
	v_mul_f32_e32 v250, v250, v192
	v_mul_f32_e32 v251, v251, v193
	v_mul_f32_e32 v116, v116, v250
	v_mul_f32_e32 v117, v117, v251
	v_lshlrev_b32_e32 v250, 16, v136
	v_and_b32_e32 v251, 0xffff0000, v136
	v_lshlrev_b32_e32 v192, 16, v238
	v_and_b32_e32 v193, 0xffff0000, v238
	v_max_f32_e32 v250, 0x0da24260, v250
	v_max_f32_e32 v251, 0x0da24260, v251
	v_rcp_f32_e32 v250, v250
	v_rcp_f32_e32 v251, v251
	v_max_f32_e32 v192, 0x0da24260, v192
	v_max_f32_e32 v193, 0x0da24260, v193
	v_mul_f32_e32 v250, v250, v192
	v_mul_f32_e32 v251, v251, v193
	v_mul_f32_e32 v106, v106, v250
	v_mul_f32_e32 v107, v107, v251
	v_lshlrev_b32_e32 v250, 16, v137
	v_and_b32_e32 v251, 0xffff0000, v137
	v_lshlrev_b32_e32 v192, 16, v239
	v_and_b32_e32 v193, 0xffff0000, v239
	v_max_f32_e32 v250, 0x0da24260, v250
	v_max_f32_e32 v251, 0x0da24260, v251
	v_rcp_f32_e32 v250, v250
	v_rcp_f32_e32 v251, v251
	v_max_f32_e32 v192, 0x0da24260, v192
	v_max_f32_e32 v193, 0x0da24260, v193
	v_mul_f32_e32 v250, v250, v192
	v_mul_f32_e32 v251, v251, v193
	v_mul_f32_e32 v108, v108, v250
	v_mul_f32_e32 v109, v109, v251
	v_mov_b32_e32 v236, v134
	v_mov_b32_e32 v237, v135
	v_mov_b32_e32 v238, v136
	v_mov_b32_e32 v239, v137
	global_load_dwordx4 v[134:137], v248, s[66:67] offset:2304
	s_waitcnt vmcnt(17)
	v_lshlrev_b32_e32 v250, 16, v138
	v_and_b32_e32 v251, 0xffff0000, v138
	v_lshlrev_b32_e32 v192, 16, v240
	v_and_b32_e32 v193, 0xffff0000, v240
	v_max_f32_e32 v250, 0x0da24260, v250
	v_max_f32_e32 v251, 0x0da24260, v251
	v_rcp_f32_e32 v250, v250
	v_rcp_f32_e32 v251, v251
	v_max_f32_e32 v192, 0x0da24260, v192
	v_max_f32_e32 v193, 0x0da24260, v193
	v_mul_f32_e32 v250, v250, v192
	v_mul_f32_e32 v251, v251, v193
	v_mul_f32_e32 v118, v118, v250
	v_mul_f32_e32 v119, v119, v251
	v_lshlrev_b32_e32 v250, 16, v139
	v_and_b32_e32 v251, 0xffff0000, v139
	v_lshlrev_b32_e32 v192, 16, v241
	v_and_b32_e32 v193, 0xffff0000, v241
	v_max_f32_e32 v250, 0x0da24260, v250
	v_max_f32_e32 v251, 0x0da24260, v251
	v_rcp_f32_e32 v250, v250
	v_rcp_f32_e32 v251, v251
	v_max_f32_e32 v192, 0x0da24260, v192
	v_max_f32_e32 v193, 0x0da24260, v193
	v_mul_f32_e32 v250, v250, v192
	v_mul_f32_e32 v251, v251, v193
	v_mul_f32_e32 v120, v120, v250
	v_mul_f32_e32 v121, v121, v251
	v_lshlrev_b32_e32 v250, 16, v140
	v_and_b32_e32 v251, 0xffff0000, v140
	v_lshlrev_b32_e32 v192, 16, v242
	v_and_b32_e32 v193, 0xffff0000, v242
	v_max_f32_e32 v250, 0x0da24260, v250
	v_max_f32_e32 v251, 0x0da24260, v251
	v_rcp_f32_e32 v250, v250
	v_rcp_f32_e32 v251, v251
	v_max_f32_e32 v192, 0x0da24260, v192
	v_max_f32_e32 v193, 0x0da24260, v193
	v_mul_f32_e32 v250, v250, v192
	v_mul_f32_e32 v251, v251, v193
	v_mul_f32_e32 v110, v110, v250
	v_mul_f32_e32 v111, v111, v251
	v_lshlrev_b32_e32 v250, 16, v141
	v_and_b32_e32 v251, 0xffff0000, v141
	v_lshlrev_b32_e32 v192, 16, v243
	v_and_b32_e32 v193, 0xffff0000, v243
	v_max_f32_e32 v250, 0x0da24260, v250
	v_max_f32_e32 v251, 0x0da24260, v251
	v_rcp_f32_e32 v250, v250
	v_rcp_f32_e32 v251, v251
	v_max_f32_e32 v192, 0x0da24260, v192
	v_max_f32_e32 v193, 0x0da24260, v193
	v_mul_f32_e32 v250, v250, v192
	v_mul_f32_e32 v251, v251, v193
	v_mul_f32_e32 v112, v112, v250
	v_mul_f32_e32 v113, v113, v251
	v_mov_b32_e32 v240, v138
	v_mov_b32_e32 v241, v139
	v_mov_b32_e32 v242, v140
	v_mov_b32_e32 v243, v141
	global_load_dwordx4 v[138:141], v248, s[68:69]
	s_waitcnt vmcnt(17)
	v_lshlrev_b32_e32 v250, 16, v142
	v_and_b32_e32 v251, 0xffff0000, v142
	v_lshlrev_b32_e32 v192, 16, v244
	v_and_b32_e32 v193, 0xffff0000, v244
	v_max_f32_e32 v250, 0x0da24260, v250
	v_max_f32_e32 v251, 0x0da24260, v251
	v_rcp_f32_e32 v250, v250
	v_rcp_f32_e32 v251, v251
	v_max_f32_e32 v192, 0x0da24260, v192
	v_max_f32_e32 v193, 0x0da24260, v193
	v_mul_f32_e32 v250, v250, v192
	v_mul_f32_e32 v251, v251, v193
	v_mul_f32_e32 v102, v102, v250
	v_mul_f32_e32 v103, v103, v251
	v_lshlrev_b32_e32 v250, 16, v143
	v_and_b32_e32 v251, 0xffff0000, v143
	v_lshlrev_b32_e32 v192, 16, v245
	v_and_b32_e32 v193, 0xffff0000, v245
	v_max_f32_e32 v250, 0x0da24260, v250
	v_max_f32_e32 v251, 0x0da24260, v251
	v_rcp_f32_e32 v250, v250
	v_rcp_f32_e32 v251, v251
	v_max_f32_e32 v192, 0x0da24260, v192
	v_max_f32_e32 v193, 0x0da24260, v193
	v_mul_f32_e32 v250, v250, v192
	v_mul_f32_e32 v251, v251, v193
	v_mul_f32_e32 v104, v104, v250
	v_mul_f32_e32 v105, v105, v251
	v_lshlrev_b32_e32 v250, 16, v144
	v_and_b32_e32 v251, 0xffff0000, v144
	v_lshlrev_b32_e32 v192, 16, v246
	v_and_b32_e32 v193, 0xffff0000, v246
	v_max_f32_e32 v250, 0x0da24260, v250
	v_max_f32_e32 v251, 0x0da24260, v251
	v_rcp_f32_e32 v250, v250
	v_rcp_f32_e32 v251, v251
	v_max_f32_e32 v192, 0x0da24260, v192
	v_max_f32_e32 v193, 0x0da24260, v193
	v_mul_f32_e32 v250, v250, v192
	v_mul_f32_e32 v251, v251, v193
	v_mul_f32_e32 v98, v98, v250
	v_mul_f32_e32 v99, v99, v251
	v_lshlrev_b32_e32 v250, 16, v145
	v_and_b32_e32 v251, 0xffff0000, v145
	v_lshlrev_b32_e32 v192, 16, v247
	v_and_b32_e32 v193, 0xffff0000, v247
	v_max_f32_e32 v250, 0x0da24260, v250
	v_max_f32_e32 v251, 0x0da24260, v251
	v_rcp_f32_e32 v250, v250
	v_rcp_f32_e32 v251, v251
	v_max_f32_e32 v192, 0x0da24260, v192
	v_max_f32_e32 v193, 0x0da24260, v193
	v_mul_f32_e32 v250, v250, v192
	v_mul_f32_e32 v251, v251, v193
	v_mul_f32_e32 v100, v100, v250
	v_mul_f32_e32 v101, v101, v251
	v_mov_b32_e32 v244, v142
	v_mov_b32_e32 v245, v143
	v_mov_b32_e32 v246, v144
	v_mov_b32_e32 v247, v145
	global_load_dwordx4 v[142:145], v248, s[68:69] offset:2048
	s_waitcnt vmcnt(16)
	v_lshlrev_b32_e32 v250, 16, v150
	v_and_b32_e32 v251, 0xffff0000, v150
	v_lshlrev_b32_e32 v192, 16, v146
	v_and_b32_e32 v193, 0xffff0000, v146
	v_max_f32_e32 v250, 0x0da24260, v250
	v_max_f32_e32 v251, 0x0da24260, v251
	v_rcp_f32_e32 v250, v250
	v_rcp_f32_e32 v251, v251
	v_max_f32_e32 v192, 0x0da24260, v192
	v_max_f32_e32 v193, 0x0da24260, v193
	v_mul_f32_e32 v250, v250, v192
	v_mul_f32_e32 v251, v251, v193
	v_mul_f32_e32 v94, v94, v250
	v_mul_f32_e32 v95, v95, v251
	v_lshlrev_b32_e32 v250, 16, v151
	v_and_b32_e32 v251, 0xffff0000, v151
	v_lshlrev_b32_e32 v192, 16, v147
	v_and_b32_e32 v193, 0xffff0000, v147
	v_max_f32_e32 v250, 0x0da24260, v250
	v_max_f32_e32 v251, 0x0da24260, v251
	v_rcp_f32_e32 v250, v250
	v_rcp_f32_e32 v251, v251
	v_max_f32_e32 v192, 0x0da24260, v192
	v_max_f32_e32 v193, 0x0da24260, v193
	v_mul_f32_e32 v250, v250, v192
	v_mul_f32_e32 v251, v251, v193
	v_mul_f32_e32 v96, v96, v250
	v_mul_f32_e32 v97, v97, v251
	v_lshlrev_b32_e32 v250, 16, v152
	v_and_b32_e32 v251, 0xffff0000, v152
	v_lshlrev_b32_e32 v192, 16, v148
	v_and_b32_e32 v193, 0xffff0000, v148
	v_max_f32_e32 v250, 0x0da24260, v250
	v_max_f32_e32 v251, 0x0da24260, v251
	v_rcp_f32_e32 v250, v250
	v_rcp_f32_e32 v251, v251
	v_max_f32_e32 v192, 0x0da24260, v192
	v_max_f32_e32 v193, 0x0da24260, v193
	v_mul_f32_e32 v250, v250, v192
	v_mul_f32_e32 v251, v251, v193
	v_mul_f32_e32 v90, v90, v250
	v_mul_f32_e32 v91, v91, v251
	v_lshlrev_b32_e32 v250, 16, v153
	v_and_b32_e32 v251, 0xffff0000, v153
	v_lshlrev_b32_e32 v192, 16, v149
	v_and_b32_e32 v193, 0xffff0000, v149
	v_max_f32_e32 v250, 0x0da24260, v250
	v_max_f32_e32 v251, 0x0da24260, v251
	v_rcp_f32_e32 v250, v250
	v_rcp_f32_e32 v251, v251
	v_max_f32_e32 v192, 0x0da24260, v192
	v_max_f32_e32 v193, 0x0da24260, v193
	v_mul_f32_e32 v250, v250, v192
	v_mul_f32_e32 v251, v251, v193
	v_mul_f32_e32 v92, v92, v250
	v_mul_f32_e32 v93, v93, v251
	global_load_dwordx4 v[150:153], v248, s[68:69] offset:256
	global_load_dwordx4 v[146:149], v248, s[68:69] offset:2304
	s_waitcnt vmcnt(16)
	v_lshlrev_b32_e32 v250, 16, v168
	v_and_b32_e32 v251, 0xffff0000, v168
	v_lshlrev_b32_e32 v192, 16, v164
	v_and_b32_e32 v193, 0xffff0000, v164
	v_max_f32_e32 v250, 0x0da24260, v250
	v_max_f32_e32 v251, 0x0da24260, v251
	v_rcp_f32_e32 v250, v250
	v_rcp_f32_e32 v251, v251
	v_max_f32_e32 v192, 0x0da24260, v192
	v_max_f32_e32 v193, 0x0da24260, v193
	v_mul_f32_e32 v250, v250, v192
	v_mul_f32_e32 v251, v251, v193
	v_mul_f32_e32 v82, v82, v250
	v_mul_f32_e32 v83, v83, v251
	v_lshlrev_b32_e32 v250, 16, v169
	v_and_b32_e32 v251, 0xffff0000, v169
	v_lshlrev_b32_e32 v192, 16, v165
	v_and_b32_e32 v193, 0xffff0000, v165
	v_max_f32_e32 v250, 0x0da24260, v250
	v_max_f32_e32 v251, 0x0da24260, v251
	v_rcp_f32_e32 v250, v250
	v_rcp_f32_e32 v251, v251
	v_max_f32_e32 v192, 0x0da24260, v192
	v_max_f32_e32 v193, 0x0da24260, v193
	v_mul_f32_e32 v250, v250, v192
	v_mul_f32_e32 v251, v251, v193
	v_mul_f32_e32 v84, v84, v250
	v_mul_f32_e32 v85, v85, v251
	v_lshlrev_b32_e32 v250, 16, v170
	v_and_b32_e32 v251, 0xffff0000, v170
	v_lshlrev_b32_e32 v192, 16, v166
	v_and_b32_e32 v193, 0xffff0000, v166
	v_max_f32_e32 v250, 0x0da24260, v250
	v_max_f32_e32 v251, 0x0da24260, v251
	v_rcp_f32_e32 v250, v250
	v_rcp_f32_e32 v251, v251
	v_max_f32_e32 v192, 0x0da24260, v192
	v_max_f32_e32 v193, 0x0da24260, v193
	v_mul_f32_e32 v250, v250, v192
	v_mul_f32_e32 v251, v251, v193
	v_mul_f32_e32 v74, v74, v250
	v_mul_f32_e32 v75, v75, v251
	v_lshlrev_b32_e32 v250, 16, v171
	v_and_b32_e32 v251, 0xffff0000, v171
	v_lshlrev_b32_e32 v192, 16, v167
	v_and_b32_e32 v193, 0xffff0000, v167
	v_max_f32_e32 v250, 0x0da24260, v250
	v_max_f32_e32 v251, 0x0da24260, v251
	v_rcp_f32_e32 v250, v250
	v_rcp_f32_e32 v251, v251
	v_max_f32_e32 v192, 0x0da24260, v192
	v_max_f32_e32 v193, 0x0da24260, v193
	v_mul_f32_e32 v250, v250, v192
	v_mul_f32_e32 v251, v251, v193
	v_mul_f32_e32 v76, v76, v250
	v_mul_f32_e32 v77, v77, v251
	global_load_dwordx4 v[168:171], v248, s[70:71]
	global_load_dwordx4 v[164:167], v248, s[70:71] offset:2048
	s_waitcnt vmcnt(16)
	v_lshlrev_b32_e32 v250, 16, v180
	v_and_b32_e32 v251, 0xffff0000, v180
	v_lshlrev_b32_e32 v192, 16, v172
	v_and_b32_e32 v193, 0xffff0000, v172
	v_max_f32_e32 v250, 0x0da24260, v250
	v_max_f32_e32 v251, 0x0da24260, v251
	v_rcp_f32_e32 v250, v250
	v_rcp_f32_e32 v251, v251
	v_max_f32_e32 v192, 0x0da24260, v192
	v_max_f32_e32 v193, 0x0da24260, v193
	v_mul_f32_e32 v250, v250, v192
	v_mul_f32_e32 v251, v251, v193
	v_mul_f32_e32 v86, v86, v250
	v_mul_f32_e32 v87, v87, v251
	v_lshlrev_b32_e32 v250, 16, v181
	v_and_b32_e32 v251, 0xffff0000, v181
	v_lshlrev_b32_e32 v192, 16, v173
	v_and_b32_e32 v193, 0xffff0000, v173
	v_max_f32_e32 v250, 0x0da24260, v250
	v_max_f32_e32 v251, 0x0da24260, v251
	v_rcp_f32_e32 v250, v250
	v_rcp_f32_e32 v251, v251
	v_max_f32_e32 v192, 0x0da24260, v192
	v_max_f32_e32 v193, 0x0da24260, v193
	v_mul_f32_e32 v250, v250, v192
	v_mul_f32_e32 v251, v251, v193
	v_mul_f32_e32 v88, v88, v250
	v_mul_f32_e32 v89, v89, v251
	v_lshlrev_b32_e32 v250, 16, v182
	v_and_b32_e32 v251, 0xffff0000, v182
	v_lshlrev_b32_e32 v192, 16, v174
	v_and_b32_e32 v193, 0xffff0000, v174
	v_max_f32_e32 v250, 0x0da24260, v250
	v_max_f32_e32 v251, 0x0da24260, v251
	v_rcp_f32_e32 v250, v250
	v_rcp_f32_e32 v251, v251
	v_max_f32_e32 v192, 0x0da24260, v192
	v_max_f32_e32 v193, 0x0da24260, v193
	v_mul_f32_e32 v250, v250, v192
	v_mul_f32_e32 v251, v251, v193
	v_mul_f32_e32 v78, v78, v250
	v_mul_f32_e32 v79, v79, v251
	v_lshlrev_b32_e32 v250, 16, v183
	v_and_b32_e32 v251, 0xffff0000, v183
	v_lshlrev_b32_e32 v192, 16, v175
	v_and_b32_e32 v193, 0xffff0000, v175
	v_max_f32_e32 v250, 0x0da24260, v250
	v_max_f32_e32 v251, 0x0da24260, v251
	v_rcp_f32_e32 v250, v250
	v_rcp_f32_e32 v251, v251
	v_max_f32_e32 v192, 0x0da24260, v192
	v_max_f32_e32 v193, 0x0da24260, v193
	v_mul_f32_e32 v250, v250, v192
	v_mul_f32_e32 v251, v251, v193
	v_mul_f32_e32 v80, v80, v250
	v_mul_f32_e32 v81, v81, v251
	global_load_dwordx4 v[180:183], v248, s[70:71] offset:256
	global_load_dwordx4 v[172:175], v248, s[70:71] offset:2304
	s_waitcnt vmcnt(16)
	v_lshlrev_b32_e32 v250, 16, v188
	v_and_b32_e32 v251, 0xffff0000, v188
	v_lshlrev_b32_e32 v192, 16, v184
	v_and_b32_e32 v193, 0xffff0000, v184
	v_max_f32_e32 v250, 0x0da24260, v250
	v_max_f32_e32 v251, 0x0da24260, v251
	v_rcp_f32_e32 v250, v250
	v_rcp_f32_e32 v251, v251
	v_max_f32_e32 v192, 0x0da24260, v192
	v_max_f32_e32 v193, 0x0da24260, v193
	v_mul_f32_e32 v250, v250, v192
	v_mul_f32_e32 v251, v251, v193
	v_mul_f32_e32 v70, v70, v250
	v_mul_f32_e32 v71, v71, v251
	v_lshlrev_b32_e32 v250, 16, v189
	v_and_b32_e32 v251, 0xffff0000, v189
	v_lshlrev_b32_e32 v192, 16, v185
	v_and_b32_e32 v193, 0xffff0000, v185
	v_max_f32_e32 v250, 0x0da24260, v250
	v_max_f32_e32 v251, 0x0da24260, v251
	v_rcp_f32_e32 v250, v250
	v_rcp_f32_e32 v251, v251
	v_max_f32_e32 v192, 0x0da24260, v192
	v_max_f32_e32 v193, 0x0da24260, v193
	v_mul_f32_e32 v250, v250, v192
	v_mul_f32_e32 v251, v251, v193
	v_mul_f32_e32 v72, v72, v250
	v_mul_f32_e32 v73, v73, v251
	v_lshlrev_b32_e32 v250, 16, v190
	v_and_b32_e32 v251, 0xffff0000, v190
	v_lshlrev_b32_e32 v192, 16, v186
	v_and_b32_e32 v193, 0xffff0000, v186
	v_max_f32_e32 v250, 0x0da24260, v250
	v_max_f32_e32 v251, 0x0da24260, v251
	v_rcp_f32_e32 v250, v250
	v_rcp_f32_e32 v251, v251
	v_max_f32_e32 v192, 0x0da24260, v192
	v_max_f32_e32 v193, 0x0da24260, v193
	v_mul_f32_e32 v250, v250, v192
	v_mul_f32_e32 v251, v251, v193
	v_mul_f32_e32 v66, v66, v250
	v_mul_f32_e32 v67, v67, v251
	v_lshlrev_b32_e32 v250, 16, v191
	v_and_b32_e32 v251, 0xffff0000, v191
	v_lshlrev_b32_e32 v192, 16, v187
	v_and_b32_e32 v193, 0xffff0000, v187
	v_max_f32_e32 v250, 0x0da24260, v250
	v_max_f32_e32 v251, 0x0da24260, v251
	v_rcp_f32_e32 v250, v250
	v_rcp_f32_e32 v251, v251
	v_max_f32_e32 v192, 0x0da24260, v192
	v_max_f32_e32 v193, 0x0da24260, v193
	v_mul_f32_e32 v250, v250, v192
	v_mul_f32_e32 v251, v251, v193
	v_mul_f32_e32 v68, v68, v250
	v_mul_f32_e32 v69, v69, v251
	s_waitcnt vmcnt(14)
	v_lshlrev_b32_e32 v250, 16, v212
	v_and_b32_e32 v251, 0xffff0000, v212
	v_lshlrev_b32_e32 v192, 16, v198
	v_and_b32_e32 v193, 0xffff0000, v198
	v_max_f32_e32 v250, 0x0da24260, v250
	v_max_f32_e32 v251, 0x0da24260, v251
	v_rcp_f32_e32 v250, v250
	v_rcp_f32_e32 v251, v251
	v_max_f32_e32 v192, 0x0da24260, v192
	v_max_f32_e32 v193, 0x0da24260, v193
	v_mul_f32_e32 v250, v250, v192
	v_mul_f32_e32 v251, v251, v193
	v_mul_f32_e32 v62, v62, v250
	v_mul_f32_e32 v63, v63, v251
	v_lshlrev_b32_e32 v250, 16, v213
	v_and_b32_e32 v251, 0xffff0000, v213
	v_lshlrev_b32_e32 v192, 16, v199
	v_and_b32_e32 v193, 0xffff0000, v199
	v_max_f32_e32 v250, 0x0da24260, v250
	v_max_f32_e32 v251, 0x0da24260, v251
	v_rcp_f32_e32 v250, v250
	v_rcp_f32_e32 v251, v251
	v_max_f32_e32 v192, 0x0da24260, v192
	v_max_f32_e32 v193, 0x0da24260, v193
	v_mul_f32_e32 v250, v250, v192
	v_mul_f32_e32 v251, v251, v193
	v_mul_f32_e32 v64, v64, v250
	v_mul_f32_e32 v65, v65, v251
	v_lshlrev_b32_e32 v250, 16, v214
	v_and_b32_e32 v251, 0xffff0000, v214
	v_lshlrev_b32_e32 v192, 16, v200
	v_and_b32_e32 v193, 0xffff0000, v200
	v_max_f32_e32 v250, 0x0da24260, v250
	v_max_f32_e32 v251, 0x0da24260, v251
	v_rcp_f32_e32 v250, v250
	v_rcp_f32_e32 v251, v251
	v_max_f32_e32 v192, 0x0da24260, v192
	v_max_f32_e32 v193, 0x0da24260, v193
	v_mul_f32_e32 v250, v250, v192
	v_mul_f32_e32 v251, v251, v193
	v_mul_f32_e32 v58, v58, v250
	v_mul_f32_e32 v59, v59, v251
	v_lshlrev_b32_e32 v250, 16, v215
	v_and_b32_e32 v251, 0xffff0000, v215
	v_lshlrev_b32_e32 v192, 16, v201
	v_and_b32_e32 v193, 0xffff0000, v201
	v_max_f32_e32 v250, 0x0da24260, v250
	v_max_f32_e32 v251, 0x0da24260, v251
	v_rcp_f32_e32 v250, v250
	v_rcp_f32_e32 v251, v251
	v_max_f32_e32 v192, 0x0da24260, v192
	v_max_f32_e32 v193, 0x0da24260, v193
	v_mul_f32_e32 v250, v250, v192
	v_mul_f32_e32 v251, v251, v193
	v_mul_f32_e32 v60, v60, v250
	v_mul_f32_e32 v61, v61, v251
	s_waitcnt vmcnt(12)
	v_lshlrev_b32_e32 v250, 16, v220
	v_and_b32_e32 v251, 0xffff0000, v220
	v_lshlrev_b32_e32 v192, 16, v216
	v_and_b32_e32 v193, 0xffff0000, v216
	v_max_f32_e32 v250, 0x0da24260, v250
	v_max_f32_e32 v251, 0x0da24260, v251
	v_rcp_f32_e32 v250, v250
	v_rcp_f32_e32 v251, v251
	v_max_f32_e32 v192, 0x0da24260, v192
	v_max_f32_e32 v193, 0x0da24260, v193
	v_mul_f32_e32 v250, v250, v192
	v_mul_f32_e32 v251, v251, v193
	v_mul_f32_e32 v50, v50, v250
	v_mul_f32_e32 v51, v51, v251
	v_lshlrev_b32_e32 v250, 16, v221
	v_and_b32_e32 v251, 0xffff0000, v221
	v_lshlrev_b32_e32 v192, 16, v217
	v_and_b32_e32 v193, 0xffff0000, v217
	v_max_f32_e32 v250, 0x0da24260, v250
	v_max_f32_e32 v251, 0x0da24260, v251
	v_rcp_f32_e32 v250, v250
	v_rcp_f32_e32 v251, v251
	v_max_f32_e32 v192, 0x0da24260, v192
	v_max_f32_e32 v193, 0x0da24260, v193
	v_mul_f32_e32 v250, v250, v192
	v_mul_f32_e32 v251, v251, v193
	v_mul_f32_e32 v52, v52, v250
	v_mul_f32_e32 v53, v53, v251
	v_lshlrev_b32_e32 v250, 16, v222
	v_and_b32_e32 v251, 0xffff0000, v222
	v_lshlrev_b32_e32 v192, 16, v218
	v_and_b32_e32 v193, 0xffff0000, v218
	v_max_f32_e32 v250, 0x0da24260, v250
	v_max_f32_e32 v251, 0x0da24260, v251
	v_rcp_f32_e32 v250, v250
	v_rcp_f32_e32 v251, v251
	v_max_f32_e32 v192, 0x0da24260, v192
	v_max_f32_e32 v193, 0x0da24260, v193
	v_mul_f32_e32 v250, v250, v192
	v_mul_f32_e32 v251, v251, v193
	v_mul_f32_e32 v42, v42, v250
	v_mul_f32_e32 v43, v43, v251
	v_lshlrev_b32_e32 v250, 16, v223
	v_and_b32_e32 v251, 0xffff0000, v223
	v_lshlrev_b32_e32 v192, 16, v219
	v_and_b32_e32 v193, 0xffff0000, v219
	v_max_f32_e32 v250, 0x0da24260, v250
	v_max_f32_e32 v251, 0x0da24260, v251
	v_rcp_f32_e32 v250, v250
	v_rcp_f32_e32 v251, v251
	v_max_f32_e32 v192, 0x0da24260, v192
	v_max_f32_e32 v193, 0x0da24260, v193
	v_mul_f32_e32 v250, v250, v192
	v_mul_f32_e32 v251, v251, v193
	v_mul_f32_e32 v44, v44, v250
	v_mul_f32_e32 v45, v45, v251
	s_waitcnt vmcnt(10)
	v_lshlrev_b32_e32 v250, 16, v228
	v_and_b32_e32 v251, 0xffff0000, v228
	v_lshlrev_b32_e32 v192, 16, v224
	v_and_b32_e32 v193, 0xffff0000, v224
	v_max_f32_e32 v250, 0x0da24260, v250
	v_max_f32_e32 v251, 0x0da24260, v251
	v_rcp_f32_e32 v250, v250
	v_rcp_f32_e32 v251, v251
	v_max_f32_e32 v192, 0x0da24260, v192
	v_max_f32_e32 v193, 0x0da24260, v193
	v_mul_f32_e32 v250, v250, v192
	v_mul_f32_e32 v251, v251, v193
	v_mul_f32_e32 v54, v54, v250
	v_mul_f32_e32 v55, v55, v251
	v_lshlrev_b32_e32 v250, 16, v229
	v_and_b32_e32 v251, 0xffff0000, v229
	v_lshlrev_b32_e32 v192, 16, v225
	v_and_b32_e32 v193, 0xffff0000, v225
	v_max_f32_e32 v250, 0x0da24260, v250
	v_max_f32_e32 v251, 0x0da24260, v251
	v_rcp_f32_e32 v250, v250
	v_rcp_f32_e32 v251, v251
	v_max_f32_e32 v192, 0x0da24260, v192
	v_max_f32_e32 v193, 0x0da24260, v193
	v_mul_f32_e32 v250, v250, v192
	v_mul_f32_e32 v251, v251, v193
	v_mul_f32_e32 v56, v56, v250
	v_mul_f32_e32 v57, v57, v251
	v_lshlrev_b32_e32 v250, 16, v230
	v_and_b32_e32 v251, 0xffff0000, v230
	v_lshlrev_b32_e32 v192, 16, v226
	v_and_b32_e32 v193, 0xffff0000, v226
	v_max_f32_e32 v250, 0x0da24260, v250
	v_max_f32_e32 v251, 0x0da24260, v251
	v_rcp_f32_e32 v250, v250
	v_rcp_f32_e32 v251, v251
	v_max_f32_e32 v192, 0x0da24260, v192
	v_max_f32_e32 v193, 0x0da24260, v193
	v_mul_f32_e32 v250, v250, v192
	v_mul_f32_e32 v251, v251, v193
	v_mul_f32_e32 v46, v46, v250
	v_mul_f32_e32 v47, v47, v251
	v_lshlrev_b32_e32 v250, 16, v231
	v_and_b32_e32 v251, 0xffff0000, v231
	v_lshlrev_b32_e32 v192, 16, v227
	v_and_b32_e32 v193, 0xffff0000, v227
	v_max_f32_e32 v250, 0x0da24260, v250
	v_max_f32_e32 v251, 0x0da24260, v251
	v_rcp_f32_e32 v250, v250
	v_rcp_f32_e32 v251, v251
	v_max_f32_e32 v192, 0x0da24260, v192
	v_max_f32_e32 v193, 0x0da24260, v193
	v_mul_f32_e32 v250, v250, v192
	v_mul_f32_e32 v251, v251, v193
	v_mul_f32_e32 v48, v48, v250
	v_mul_f32_e32 v49, v49, v251
	s_waitcnt vmcnt(8)
	v_lshlrev_b32_e32 v250, 16, v134
	v_and_b32_e32 v251, 0xffff0000, v134
	v_lshlrev_b32_e32 v192, 16, v130
	v_and_b32_e32 v193, 0xffff0000, v130
	v_max_f32_e32 v250, 0x0da24260, v250
	v_max_f32_e32 v251, 0x0da24260, v251
	v_rcp_f32_e32 v250, v250
	v_rcp_f32_e32 v251, v251
	v_max_f32_e32 v192, 0x0da24260, v192
	v_max_f32_e32 v193, 0x0da24260, v193
	v_mul_f32_e32 v250, v250, v192
	v_mul_f32_e32 v251, v251, v193
	v_mul_f32_e32 v38, v38, v250
	v_mul_f32_e32 v39, v39, v251
	v_lshlrev_b32_e32 v250, 16, v135
	v_and_b32_e32 v251, 0xffff0000, v135
	v_lshlrev_b32_e32 v192, 16, v131
	v_and_b32_e32 v193, 0xffff0000, v131
	v_max_f32_e32 v250, 0x0da24260, v250
	v_max_f32_e32 v251, 0x0da24260, v251
	v_rcp_f32_e32 v250, v250
	v_rcp_f32_e32 v251, v251
	v_max_f32_e32 v192, 0x0da24260, v192
	v_max_f32_e32 v193, 0x0da24260, v193
	v_mul_f32_e32 v250, v250, v192
	v_mul_f32_e32 v251, v251, v193
	v_mul_f32_e32 v40, v40, v250
	v_mul_f32_e32 v41, v41, v251
	v_lshlrev_b32_e32 v250, 16, v136
	v_and_b32_e32 v251, 0xffff0000, v136
	v_lshlrev_b32_e32 v192, 16, v132
	v_and_b32_e32 v193, 0xffff0000, v132
	v_max_f32_e32 v250, 0x0da24260, v250
	v_max_f32_e32 v251, 0x0da24260, v251
	v_rcp_f32_e32 v250, v250
	v_rcp_f32_e32 v251, v251
	v_max_f32_e32 v192, 0x0da24260, v192
	v_max_f32_e32 v193, 0x0da24260, v193
	v_mul_f32_e32 v250, v250, v192
	v_mul_f32_e32 v251, v251, v193
	v_mul_f32_e32 v34, v34, v250
	v_mul_f32_e32 v35, v35, v251
	v_lshlrev_b32_e32 v250, 16, v137
	v_and_b32_e32 v251, 0xffff0000, v137
	v_lshlrev_b32_e32 v192, 16, v133
	v_and_b32_e32 v193, 0xffff0000, v133
	v_max_f32_e32 v250, 0x0da24260, v250
	v_max_f32_e32 v251, 0x0da24260, v251
	v_rcp_f32_e32 v250, v250
	v_rcp_f32_e32 v251, v251
	v_max_f32_e32 v192, 0x0da24260, v192
	v_max_f32_e32 v193, 0x0da24260, v193
	v_mul_f32_e32 v250, v250, v192
	v_mul_f32_e32 v251, v251, v193
	v_mul_f32_e32 v36, v36, v250
	v_mul_f32_e32 v37, v37, v251
	s_waitcnt vmcnt(6)
	v_lshlrev_b32_e32 v250, 16, v142
	v_and_b32_e32 v251, 0xffff0000, v142
	v_lshlrev_b32_e32 v192, 16, v138
	v_and_b32_e32 v193, 0xffff0000, v138
	v_max_f32_e32 v250, 0x0da24260, v250
	v_max_f32_e32 v251, 0x0da24260, v251
	v_rcp_f32_e32 v250, v250
	v_rcp_f32_e32 v251, v251
	v_max_f32_e32 v192, 0x0da24260, v192
	v_max_f32_e32 v193, 0x0da24260, v193
	v_mul_f32_e32 v250, v250, v192
	v_mul_f32_e32 v251, v251, v193
	v_mul_f32_e32 v30, v30, v250
	v_mul_f32_e32 v31, v31, v251
	v_lshlrev_b32_e32 v250, 16, v143
	v_and_b32_e32 v251, 0xffff0000, v143
	v_lshlrev_b32_e32 v192, 16, v139
	v_and_b32_e32 v193, 0xffff0000, v139
	v_max_f32_e32 v250, 0x0da24260, v250
	v_max_f32_e32 v251, 0x0da24260, v251
	v_rcp_f32_e32 v250, v250
	v_rcp_f32_e32 v251, v251
	v_max_f32_e32 v192, 0x0da24260, v192
	v_max_f32_e32 v193, 0x0da24260, v193
	v_mul_f32_e32 v250, v250, v192
	v_mul_f32_e32 v251, v251, v193
	v_mul_f32_e32 v32, v32, v250
	v_mul_f32_e32 v33, v33, v251
	v_lshlrev_b32_e32 v250, 16, v144
	v_and_b32_e32 v251, 0xffff0000, v144
	v_lshlrev_b32_e32 v192, 16, v140
	v_and_b32_e32 v193, 0xffff0000, v140
	v_max_f32_e32 v250, 0x0da24260, v250
	v_max_f32_e32 v251, 0x0da24260, v251
	v_rcp_f32_e32 v250, v250
	v_rcp_f32_e32 v251, v251
	v_max_f32_e32 v192, 0x0da24260, v192
	v_max_f32_e32 v193, 0x0da24260, v193
	v_mul_f32_e32 v250, v250, v192
	v_mul_f32_e32 v251, v251, v193
	v_mul_f32_e32 v26, v26, v250
	v_mul_f32_e32 v27, v27, v251
	v_lshlrev_b32_e32 v250, 16, v145
	v_and_b32_e32 v251, 0xffff0000, v145
	v_lshlrev_b32_e32 v192, 16, v141
	v_and_b32_e32 v193, 0xffff0000, v141
	v_max_f32_e32 v250, 0x0da24260, v250
	v_max_f32_e32 v251, 0x0da24260, v251
	v_rcp_f32_e32 v250, v250
	v_rcp_f32_e32 v251, v251
	v_max_f32_e32 v192, 0x0da24260, v192
	v_max_f32_e32 v193, 0x0da24260, v193
	v_mul_f32_e32 v250, v250, v192
	v_mul_f32_e32 v251, v251, v193
	v_mul_f32_e32 v28, v28, v250
	v_mul_f32_e32 v29, v29, v251
	s_waitcnt vmcnt(4)
	v_lshlrev_b32_e32 v250, 16, v146
	v_and_b32_e32 v251, 0xffff0000, v146
	v_lshlrev_b32_e32 v192, 16, v150
	v_and_b32_e32 v193, 0xffff0000, v150
	v_max_f32_e32 v250, 0x0da24260, v250
	v_max_f32_e32 v251, 0x0da24260, v251
	v_rcp_f32_e32 v250, v250
	v_rcp_f32_e32 v251, v251
	v_max_f32_e32 v192, 0x0da24260, v192
	v_max_f32_e32 v193, 0x0da24260, v193
	v_mul_f32_e32 v250, v250, v192
	v_mul_f32_e32 v251, v251, v193
	v_mul_f32_e32 v18, v18, v250
	v_mul_f32_e32 v19, v19, v251
	v_lshlrev_b32_e32 v250, 16, v147
	v_and_b32_e32 v251, 0xffff0000, v147
	v_lshlrev_b32_e32 v192, 16, v151
	v_and_b32_e32 v193, 0xffff0000, v151
	v_max_f32_e32 v250, 0x0da24260, v250
	v_max_f32_e32 v251, 0x0da24260, v251
	v_rcp_f32_e32 v250, v250
	v_rcp_f32_e32 v251, v251
	v_max_f32_e32 v192, 0x0da24260, v192
	v_max_f32_e32 v193, 0x0da24260, v193
	v_mul_f32_e32 v250, v250, v192
	v_mul_f32_e32 v251, v251, v193
	v_mul_f32_e32 v20, v20, v250
	v_mul_f32_e32 v21, v21, v251
	v_lshlrev_b32_e32 v250, 16, v148
	v_and_b32_e32 v251, 0xffff0000, v148
	v_lshlrev_b32_e32 v192, 16, v152
	v_and_b32_e32 v193, 0xffff0000, v152
	v_max_f32_e32 v250, 0x0da24260, v250
	v_max_f32_e32 v251, 0x0da24260, v251
	v_rcp_f32_e32 v250, v250
	v_rcp_f32_e32 v251, v251
	v_max_f32_e32 v192, 0x0da24260, v192
	v_max_f32_e32 v193, 0x0da24260, v193
	v_mul_f32_e32 v250, v250, v192
	v_mul_f32_e32 v251, v251, v193
	v_mul_f32_e32 v10, v10, v250
	v_mul_f32_e32 v11, v11, v251
	v_lshlrev_b32_e32 v250, 16, v149
	v_and_b32_e32 v251, 0xffff0000, v149
	v_lshlrev_b32_e32 v192, 16, v153
	v_and_b32_e32 v193, 0xffff0000, v153
	v_max_f32_e32 v250, 0x0da24260, v250
	v_max_f32_e32 v251, 0x0da24260, v251
	v_rcp_f32_e32 v250, v250
	v_rcp_f32_e32 v251, v251
	v_max_f32_e32 v192, 0x0da24260, v192
	v_max_f32_e32 v193, 0x0da24260, v193
	v_mul_f32_e32 v250, v250, v192
	v_mul_f32_e32 v251, v251, v193
	v_mul_f32_e32 v12, v12, v250
	v_mul_f32_e32 v13, v13, v251
	s_waitcnt vmcnt(2)
	v_lshlrev_b32_e32 v250, 16, v164
	v_and_b32_e32 v251, 0xffff0000, v164
	v_lshlrev_b32_e32 v192, 16, v168
	v_and_b32_e32 v193, 0xffff0000, v168
	v_max_f32_e32 v250, 0x0da24260, v250
	v_max_f32_e32 v251, 0x0da24260, v251
	v_rcp_f32_e32 v250, v250
	v_rcp_f32_e32 v251, v251
	v_max_f32_e32 v192, 0x0da24260, v192
	v_max_f32_e32 v193, 0x0da24260, v193
	v_mul_f32_e32 v250, v250, v192
	v_mul_f32_e32 v251, v251, v193
	v_mul_f32_e32 v22, v22, v250
	v_mul_f32_e32 v23, v23, v251
	v_lshlrev_b32_e32 v250, 16, v165
	v_and_b32_e32 v251, 0xffff0000, v165
	v_lshlrev_b32_e32 v192, 16, v169
	v_and_b32_e32 v193, 0xffff0000, v169
	v_max_f32_e32 v250, 0x0da24260, v250
	v_max_f32_e32 v251, 0x0da24260, v251
	v_rcp_f32_e32 v250, v250
	v_rcp_f32_e32 v251, v251
	v_max_f32_e32 v192, 0x0da24260, v192
	v_max_f32_e32 v193, 0x0da24260, v193
	v_mul_f32_e32 v250, v250, v192
	v_mul_f32_e32 v251, v251, v193
	v_mul_f32_e32 v24, v24, v250
	v_mul_f32_e32 v25, v25, v251
	v_lshlrev_b32_e32 v250, 16, v166
	v_and_b32_e32 v251, 0xffff0000, v166
	v_lshlrev_b32_e32 v192, 16, v170
	v_and_b32_e32 v193, 0xffff0000, v170
	v_max_f32_e32 v250, 0x0da24260, v250
	v_max_f32_e32 v251, 0x0da24260, v251
	v_rcp_f32_e32 v250, v250
	v_rcp_f32_e32 v251, v251
	v_max_f32_e32 v192, 0x0da24260, v192
	v_max_f32_e32 v193, 0x0da24260, v193
	v_mul_f32_e32 v250, v250, v192
	v_mul_f32_e32 v251, v251, v193
	v_mul_f32_e32 v14, v14, v250
	v_mul_f32_e32 v15, v15, v251
	v_lshlrev_b32_e32 v250, 16, v167
	v_and_b32_e32 v251, 0xffff0000, v167
	v_lshlrev_b32_e32 v192, 16, v171
	v_and_b32_e32 v193, 0xffff0000, v171
	v_max_f32_e32 v250, 0x0da24260, v250
	v_max_f32_e32 v251, 0x0da24260, v251
	v_rcp_f32_e32 v250, v250
	v_rcp_f32_e32 v251, v251
	v_max_f32_e32 v192, 0x0da24260, v192
	v_max_f32_e32 v193, 0x0da24260, v193
	v_mul_f32_e32 v250, v250, v192
	v_mul_f32_e32 v251, v251, v193
	v_mul_f32_e32 v16, v16, v250
	v_mul_f32_e32 v17, v17, v251
	s_waitcnt vmcnt(0)
	v_lshlrev_b32_e32 v250, 16, v172
	v_and_b32_e32 v251, 0xffff0000, v172
	v_lshlrev_b32_e32 v192, 16, v180
	v_and_b32_e32 v193, 0xffff0000, v180
	v_max_f32_e32 v250, 0x0da24260, v250
	v_max_f32_e32 v251, 0x0da24260, v251
	v_rcp_f32_e32 v250, v250
	v_rcp_f32_e32 v251, v251
	v_max_f32_e32 v192, 0x0da24260, v192
	v_max_f32_e32 v193, 0x0da24260, v193
	v_mul_f32_e32 v250, v250, v192
	v_mul_f32_e32 v251, v251, v193
	v_mul_f32_e32 v6, v6, v250
	v_mul_f32_e32 v7, v7, v251
	v_lshlrev_b32_e32 v250, 16, v173
	v_and_b32_e32 v251, 0xffff0000, v173
	v_lshlrev_b32_e32 v192, 16, v181
	v_and_b32_e32 v193, 0xffff0000, v181
	v_max_f32_e32 v250, 0x0da24260, v250
	v_max_f32_e32 v251, 0x0da24260, v251
	v_rcp_f32_e32 v250, v250
	v_rcp_f32_e32 v251, v251
	v_max_f32_e32 v192, 0x0da24260, v192
	v_max_f32_e32 v193, 0x0da24260, v193
	v_mul_f32_e32 v250, v250, v192
	v_mul_f32_e32 v251, v251, v193
	v_mul_f32_e32 v8, v8, v250
	v_mul_f32_e32 v9, v9, v251
	v_lshlrev_b32_e32 v250, 16, v174
	v_and_b32_e32 v251, 0xffff0000, v174
	v_lshlrev_b32_e32 v192, 16, v182
	v_and_b32_e32 v193, 0xffff0000, v182
	v_max_f32_e32 v250, 0x0da24260, v250
	v_max_f32_e32 v251, 0x0da24260, v251
	v_rcp_f32_e32 v250, v250
	v_rcp_f32_e32 v251, v251
	v_max_f32_e32 v192, 0x0da24260, v192
	v_max_f32_e32 v193, 0x0da24260, v193
	v_mul_f32_e32 v250, v250, v192
	v_mul_f32_e32 v251, v251, v193
	v_mul_f32_e32 v2, v2, v250
	v_mul_f32_e32 v3, v3, v251
	v_lshlrev_b32_e32 v250, 16, v175
	v_and_b32_e32 v251, 0xffff0000, v175
	v_lshlrev_b32_e32 v192, 16, v183
	v_and_b32_e32 v193, 0xffff0000, v183
	v_max_f32_e32 v250, 0x0da24260, v250
	v_max_f32_e32 v251, 0x0da24260, v251
	v_rcp_f32_e32 v250, v250
	v_rcp_f32_e32 v251, v251
	v_max_f32_e32 v192, 0x0da24260, v192
	v_max_f32_e32 v193, 0x0da24260, v193
	v_mul_f32_e32 v250, v250, v192
	v_mul_f32_e32 v251, v251, v193
	v_mul_f32_e32 v4, v4, v250
	v_mul_f32_e32 v5, v5, v251
	s_branch .Lm_done
.Lm_final:
	global_load_dwordx4 v[130:133], v248, s[60:61]
	global_load_dwordx4 v[134:137], v248, s[60:61] offset:256
	global_load_dwordx4 v[138:141], v248, s[62:63]
	global_load_dwordx4 v[142:145], v248, s[62:63] offset:256
	global_load_dwordx4 v[146:149], v248, s[64:65]
	global_load_dwordx4 v[150:153], v248, s[64:65] offset:256
	global_load_dwordx4 v[164:167], v248, s[66:67]
	global_load_dwordx4 v[168:171], v248, s[66:67] offset:256
	global_load_dwordx4 v[172:175], v248, s[68:69]
	global_load_dwordx4 v[180:183], v248, s[68:69] offset:256
	global_load_dwordx4 v[184:187], v248, s[70:71]
	global_load_dwordx4 v[188:191], v248, s[70:71] offset:256
	v_lshlrev_b32_e32 v250, 16, v232
	v_and_b32_e32 v232, 0xffff0000, v232
	v_lshlrev_b32_e32 v192, 16, v233
	v_and_b32_e32 v233, 0xffff0000, v233
	v_max_f32_e32 v250, 0x0da24260, v250
	v_max_f32_e32 v232, 0x0da24260, v232
	v_max_f32_e32 v192, 0x0da24260, v192
	v_max_f32_e32 v233, 0x0da24260, v233
	v_mul_f32_e32 v250, v126, v250
	v_mul_f32_e32 v232, v127, v232
	v_mul_f32_e32 v192, v128, v192
	v_mul_f32_e32 v233, v129, v233
	v_cvt_pk_bf16_f32 v232, v250, v232
	v_cvt_pk_bf16_f32 v233, v192, v233
	v_lshlrev_b32_e32 v250, 16, v234
	v_and_b32_e32 v234, 0xffff0000, v234
	v_lshlrev_b32_e32 v192, 16, v235
	v_and_b32_e32 v235, 0xffff0000, v235
	v_max_f32_e32 v250, 0x0da24260, v250
	v_max_f32_e32 v234, 0x0da24260, v234
	v_max_f32_e32 v192, 0x0da24260, v192
	v_max_f32_e32 v235, 0x0da24260, v235
	v_mul_f32_e32 v250, v122, v250
	v_mul_f32_e32 v234, v123, v234
	v_mul_f32_e32 v192, v124, v192
	v_mul_f32_e32 v235, v125, v235
	v_cvt_pk_bf16_f32 v234, v250, v234
	v_cvt_pk_bf16_f32 v235, v192, v235
	global_store_dwordx4 v249, v[232:235], s[82:83]
	v_lshlrev_b32_e32 v250, 16, v236
	v_and_b32_e32 v236, 0xffff0000, v236
	v_lshlrev_b32_e32 v192, 16, v237
	v_and_b32_e32 v237, 0xffff0000, v237
	v_max_f32_e32 v250, 0x0da24260, v250
	v_max_f32_e32 v236, 0x0da24260, v236
	v_max_f32_e32 v192, 0x0da24260, v192
	v_max_f32_e32 v237, 0x0da24260, v237
	v_mul_f32_e32 v250, v114, v250
	v_mul_f32_e32 v236, v115, v236
	v_mul_f32_e32 v192, v116, v192
	v_mul_f32_e32 v237, v117, v237
	v_cvt_pk_bf16_f32 v236, v250, v236
	v_cvt_pk_bf16_f32 v237, v192, v237
	v_lshlrev_b32_e32 v250, 16, v238
	v_and_b32_e32 v238, 0xffff0000, v238
	v_lshlrev_b32_e32 v192, 16, v239
	v_and_b32_e32 v239, 0xffff0000, v239
	v_max_f32_e32 v250, 0x0da24260, v250
	v_max_f32_e32 v238, 0x0da24260, v238
	v_max_f32_e32 v192, 0x0da24260, v192
	v_max_f32_e32 v239, 0x0da24260, v239
	v_mul_f32_e32 v250, v106, v250
	v_mul_f32_e32 v238, v107, v238
	v_mul_f32_e32 v192, v108, v192
	v_mul_f32_e32 v239, v109, v239
	v_cvt_pk_bf16_f32 v238, v250, v238
	v_cvt_pk_bf16_f32 v239, v192, v239
	global_store_dwordx4 v249, v[236:239], s[82:83] offset:256
	v_lshlrev_b32_e32 v250, 16, v240
	v_and_b32_e32 v240, 0xffff0000, v240
	v_lshlrev_b32_e32 v192, 16, v241
	v_and_b32_e32 v241, 0xffff0000, v241
	v_max_f32_e32 v250, 0x0da24260, v250
	v_max_f32_e32 v240, 0x0da24260, v240
	v_max_f32_e32 v192, 0x0da24260, v192
	v_max_f32_e32 v241, 0x0da24260, v241
	v_mul_f32_e32 v250, v118, v250
	v_mul_f32_e32 v240, v119, v240
	v_mul_f32_e32 v192, v120, v192
	v_mul_f32_e32 v241, v121, v241
	v_cvt_pk_bf16_f32 v240, v250, v240
	v_cvt_pk_bf16_f32 v241, v192, v241
	v_lshlrev_b32_e32 v250, 16, v242
	v_and_b32_e32 v242, 0xffff0000, v242
	v_lshlrev_b32_e32 v192, 16, v243
	v_and_b32_e32 v243, 0xffff0000, v243
	v_max_f32_e32 v250, 0x0da24260, v250
	v_max_f32_e32 v242, 0x0da24260, v242
	v_max_f32_e32 v192, 0x0da24260, v192
	v_max_f32_e32 v243, 0x0da24260, v243
	v_mul_f32_e32 v250, v110, v250
	v_mul_f32_e32 v242, v111, v242
	v_mul_f32_e32 v192, v112, v192
	v_mul_f32_e32 v243, v113, v243
	v_cvt_pk_bf16_f32 v242, v250, v242
	v_cvt_pk_bf16_f32 v243, v192, v243
	global_store_dwordx4 v249, v[240:243], s[84:85]
	v_lshlrev_b32_e32 v250, 16, v244
	v_and_b32_e32 v244, 0xffff0000, v244
	v_lshlrev_b32_e32 v192, 16, v245
	v_and_b32_e32 v245, 0xffff0000, v245
	v_max_f32_e32 v250, 0x0da24260, v250
	v_max_f32_e32 v244, 0x0da24260, v244
	v_max_f32_e32 v192, 0x0da24260, v192
	v_max_f32_e32 v245, 0x0da24260, v245
	v_mul_f32_e32 v250, v102, v250
	v_mul_f32_e32 v244, v103, v244
	v_mul_f32_e32 v192, v104, v192
	v_mul_f32_e32 v245, v105, v245
	v_cvt_pk_bf16_f32 v244, v250, v244
	v_cvt_pk_bf16_f32 v245, v192, v245
	v_lshlrev_b32_e32 v250, 16, v246
	v_and_b32_e32 v246, 0xffff0000, v246
	v_lshlrev_b32_e32 v192, 16, v247
	v_and_b32_e32 v247, 0xffff0000, v247
	v_max_f32_e32 v250, 0x0da24260, v250
	v_max_f32_e32 v246, 0x0da24260, v246
	v_max_f32_e32 v192, 0x0da24260, v192
	v_max_f32_e32 v247, 0x0da24260, v247
	v_mul_f32_e32 v250, v98, v250
	v_mul_f32_e32 v246, v99, v246
	v_mul_f32_e32 v192, v100, v192
	v_mul_f32_e32 v247, v101, v247
	v_cvt_pk_bf16_f32 v246, v250, v246
	v_cvt_pk_bf16_f32 v247, v192, v247
	global_store_dwordx4 v249, v[244:247], s[84:85] offset:256
	s_waitcnt vmcnt(15)
	v_lshlrev_b32_e32 v250, 16, v130
	v_and_b32_e32 v130, 0xffff0000, v130
	v_lshlrev_b32_e32 v192, 16, v131
	v_and_b32_e32 v131, 0xffff0000, v131
	v_max_f32_e32 v250, 0x0da24260, v250
	v_max_f32_e32 v130, 0x0da24260, v130
	v_max_f32_e32 v192, 0x0da24260, v192
	v_max_f32_e32 v131, 0x0da24260, v131
	v_mul_f32_e32 v250, v94, v250
	v_mul_f32_e32 v130, v95, v130
	v_mul_f32_e32 v192, v96, v192
	v_mul_f32_e32 v131, v97, v131
	v_cvt_pk_bf16_f32 v130, v250, v130
	v_cvt_pk_bf16_f32 v131, v192, v131
	v_lshlrev_b32_e32 v250, 16, v132
	v_and_b32_e32 v132, 0xffff0000, v132
	v_lshlrev_b32_e32 v192, 16, v133
	v_and_b32_e32 v133, 0xffff0000, v133
	v_max_f32_e32 v250, 0x0da24260, v250
	v_max_f32_e32 v132, 0x0da24260, v132
	v_max_f32_e32 v192, 0x0da24260, v192
	v_max_f32_e32 v133, 0x0da24260, v133
	v_mul_f32_e32 v250, v90, v250
	v_mul_f32_e32 v132, v91, v132
	v_mul_f32_e32 v192, v92, v192
	v_mul_f32_e32 v133, v93, v133
	v_cvt_pk_bf16_f32 v132, v250, v132
	v_cvt_pk_bf16_f32 v133, v192, v133
	global_store_dwordx4 v249, v[130:133], s[86:87]
	s_waitcnt vmcnt(15)
	v_lshlrev_b32_e32 v250, 16, v134
	v_and_b32_e32 v134, 0xffff0000, v134
	v_lshlrev_b32_e32 v192, 16, v135
	v_and_b32_e32 v135, 0xffff0000, v135
	v_max_f32_e32 v250, 0x0da24260, v250
	v_max_f32_e32 v134, 0x0da24260, v134
	v_max_f32_e32 v192, 0x0da24260, v192
	v_max_f32_e32 v135, 0x0da24260, v135
	v_mul_f32_e32 v250, v82, v250
	v_mul_f32_e32 v134, v83, v134
	v_mul_f32_e32 v192, v84, v192
	v_mul_f32_e32 v135, v85, v135
	v_cvt_pk_bf16_f32 v134, v250, v134
	v_cvt_pk_bf16_f32 v135, v192, v135
	v_lshlrev_b32_e32 v250, 16, v136
	v_and_b32_e32 v136, 0xffff0000, v136
	v_lshlrev_b32_e32 v192, 16, v137
	v_and_b32_e32 v137, 0xffff0000, v137
	v_max_f32_e32 v250, 0x0da24260, v250
	v_max_f32_e32 v136, 0x0da24260, v136
	v_max_f32_e32 v192, 0x0da24260, v192
	v_max_f32_e32 v137, 0x0da24260, v137
	v_mul_f32_e32 v250, v74, v250
	v_mul_f32_e32 v136, v75, v136
	v_mul_f32_e32 v192, v76, v192
	v_mul_f32_e32 v137, v77, v137
	v_cvt_pk_bf16_f32 v136, v250, v136
	v_cvt_pk_bf16_f32 v137, v192, v137
	global_store_dwordx4 v249, v[134:137], s[86:87] offset:256
	s_waitcnt vmcnt(15)
	v_lshlrev_b32_e32 v250, 16, v138
	v_and_b32_e32 v138, 0xffff0000, v138
	v_lshlrev_b32_e32 v192, 16, v139
	v_and_b32_e32 v139, 0xffff0000, v139
	v_max_f32_e32 v250, 0x0da24260, v250
	v_max_f32_e32 v138, 0x0da24260, v138
	v_max_f32_e32 v192, 0x0da24260, v192
	v_max_f32_e32 v139, 0x0da24260, v139
	v_mul_f32_e32 v250, v86, v250
	v_mul_f32_e32 v138, v87, v138
	v_mul_f32_e32 v192, v88, v192
	v_mul_f32_e32 v139, v89, v139
	v_cvt_pk_bf16_f32 v138, v250, v138
	v_cvt_pk_bf16_f32 v139, v192, v139
	v_lshlrev_b32_e32 v250, 16, v140
	v_and_b32_e32 v140, 0xffff0000, v140
	v_lshlrev_b32_e32 v192, 16, v141
	v_and_b32_e32 v141, 0xffff0000, v141
	v_max_f32_e32 v250, 0x0da24260, v250
	v_max_f32_e32 v140, 0x0da24260, v140
	v_max_f32_e32 v192, 0x0da24260, v192
	v_max_f32_e32 v141, 0x0da24260, v141
	v_mul_f32_e32 v250, v78, v250
	v_mul_f32_e32 v140, v79, v140
	v_mul_f32_e32 v192, v80, v192
	v_mul_f32_e32 v141, v81, v141
	v_cvt_pk_bf16_f32 v140, v250, v140
	v_cvt_pk_bf16_f32 v141, v192, v141
	global_store_dwordx4 v249, v[138:141], s[88:89]
	s_waitcnt vmcnt(15)
	v_lshlrev_b32_e32 v250, 16, v142
	v_and_b32_e32 v142, 0xffff0000, v142
	v_lshlrev_b32_e32 v192, 16, v143
	v_and_b32_e32 v143, 0xffff0000, v143
	v_max_f32_e32 v250, 0x0da24260, v250
	v_max_f32_e32 v142, 0x0da24260, v142
	v_max_f32_e32 v192, 0x0da24260, v192
	v_max_f32_e32 v143, 0x0da24260, v143
	v_mul_f32_e32 v250, v70, v250
	v_mul_f32_e32 v142, v71, v142
	v_mul_f32_e32 v192, v72, v192
	v_mul_f32_e32 v143, v73, v143
	v_cvt_pk_bf16_f32 v142, v250, v142
	v_cvt_pk_bf16_f32 v143, v192, v143
	v_lshlrev_b32_e32 v250, 16, v144
	v_and_b32_e32 v144, 0xffff0000, v144
	v_lshlrev_b32_e32 v192, 16, v145
	v_and_b32_e32 v145, 0xffff0000, v145
	v_max_f32_e32 v250, 0x0da24260, v250
	v_max_f32_e32 v144, 0x0da24260, v144
	v_max_f32_e32 v192, 0x0da24260, v192
	v_max_f32_e32 v145, 0x0da24260, v145
	v_mul_f32_e32 v250, v66, v250
	v_mul_f32_e32 v144, v67, v144
	v_mul_f32_e32 v192, v68, v192
	v_mul_f32_e32 v145, v69, v145
	v_cvt_pk_bf16_f32 v144, v250, v144
	v_cvt_pk_bf16_f32 v145, v192, v145
	global_store_dwordx4 v249, v[142:145], s[88:89] offset:256
	s_waitcnt vmcnt(15)
	v_lshlrev_b32_e32 v250, 16, v146
	v_and_b32_e32 v146, 0xffff0000, v146
	v_lshlrev_b32_e32 v192, 16, v147
	v_and_b32_e32 v147, 0xffff0000, v147
	v_max_f32_e32 v250, 0x0da24260, v250
	v_max_f32_e32 v146, 0x0da24260, v146
	v_max_f32_e32 v192, 0x0da24260, v192
	v_max_f32_e32 v147, 0x0da24260, v147
	v_mul_f32_e32 v250, v62, v250
	v_mul_f32_e32 v146, v63, v146
	v_mul_f32_e32 v192, v64, v192
	v_mul_f32_e32 v147, v65, v147
	v_cvt_pk_bf16_f32 v146, v250, v146
	v_cvt_pk_bf16_f32 v147, v192, v147
	v_lshlrev_b32_e32 v250, 16, v148
	v_and_b32_e32 v148, 0xffff0000, v148
	v_lshlrev_b32_e32 v192, 16, v149
	v_and_b32_e32 v149, 0xffff0000, v149
	v_max_f32_e32 v250, 0x0da24260, v250
	v_max_f32_e32 v148, 0x0da24260, v148
	v_max_f32_e32 v192, 0x0da24260, v192
	v_max_f32_e32 v149, 0x0da24260, v149
	v_mul_f32_e32 v250, v58, v250
	v_mul_f32_e32 v148, v59, v148
	v_mul_f32_e32 v192, v60, v192
	v_mul_f32_e32 v149, v61, v149
	v_cvt_pk_bf16_f32 v148, v250, v148
	v_cvt_pk_bf16_f32 v149, v192, v149
	global_store_dwordx4 v249, v[146:149], s[90:91]
	s_waitcnt vmcnt(15)
	v_lshlrev_b32_e32 v250, 16, v150
	v_and_b32_e32 v150, 0xffff0000, v150
	v_lshlrev_b32_e32 v192, 16, v151
	v_and_b32_e32 v151, 0xffff0000, v151
	v_max_f32_e32 v250, 0x0da24260, v250
	v_max_f32_e32 v150, 0x0da24260, v150
	v_max_f32_e32 v192, 0x0da24260, v192
	v_max_f32_e32 v151, 0x0da24260, v151
	v_mul_f32_e32 v250, v50, v250
	v_mul_f32_e32 v150, v51, v150
	v_mul_f32_e32 v192, v52, v192
	v_mul_f32_e32 v151, v53, v151
	v_cvt_pk_bf16_f32 v150, v250, v150
	v_cvt_pk_bf16_f32 v151, v192, v151
	v_lshlrev_b32_e32 v250, 16, v152
	v_and_b32_e32 v152, 0xffff0000, v152
	v_lshlrev_b32_e32 v192, 16, v153
	v_and_b32_e32 v153, 0xffff0000, v153
	v_max_f32_e32 v250, 0x0da24260, v250
	v_max_f32_e32 v152, 0x0da24260, v152
	v_max_f32_e32 v192, 0x0da24260, v192
	v_max_f32_e32 v153, 0x0da24260, v153
	v_mul_f32_e32 v250, v42, v250
	v_mul_f32_e32 v152, v43, v152
	v_mul_f32_e32 v192, v44, v192
	v_mul_f32_e32 v153, v45, v153
	v_cvt_pk_bf16_f32 v152, v250, v152
	v_cvt_pk_bf16_f32 v153, v192, v153
	global_store_dwordx4 v249, v[150:153], s[90:91] offset:256
	s_waitcnt vmcnt(15)
	v_lshlrev_b32_e32 v250, 16, v164
	v_and_b32_e32 v164, 0xffff0000, v164
	v_lshlrev_b32_e32 v192, 16, v165
	v_and_b32_e32 v165, 0xffff0000, v165
	v_max_f32_e32 v250, 0x0da24260, v250
	v_max_f32_e32 v164, 0x0da24260, v164
	v_max_f32_e32 v192, 0x0da24260, v192
	v_max_f32_e32 v165, 0x0da24260, v165
	v_mul_f32_e32 v250, v54, v250
	v_mul_f32_e32 v164, v55, v164
	v_mul_f32_e32 v192, v56, v192
	v_mul_f32_e32 v165, v57, v165
	v_cvt_pk_bf16_f32 v164, v250, v164
	v_cvt_pk_bf16_f32 v165, v192, v165
	v_lshlrev_b32_e32 v250, 16, v166
	v_and_b32_e32 v166, 0xffff0000, v166
	v_lshlrev_b32_e32 v192, 16, v167
	v_and_b32_e32 v167, 0xffff0000, v167
	v_max_f32_e32 v250, 0x0da24260, v250
	v_max_f32_e32 v166, 0x0da24260, v166
	v_max_f32_e32 v192, 0x0da24260, v192
	v_max_f32_e32 v167, 0x0da24260, v167
	v_mul_f32_e32 v250, v46, v250
	v_mul_f32_e32 v166, v47, v166
	v_mul_f32_e32 v192, v48, v192
	v_mul_f32_e32 v167, v49, v167
	v_cvt_pk_bf16_f32 v166, v250, v166
	v_cvt_pk_bf16_f32 v167, v192, v167
	global_store_dwordx4 v249, v[164:167], s[92:93]
	s_waitcnt vmcnt(15)
	v_lshlrev_b32_e32 v250, 16, v168
	v_and_b32_e32 v168, 0xffff0000, v168
	v_lshlrev_b32_e32 v192, 16, v169
	v_and_b32_e32 v169, 0xffff0000, v169
	v_max_f32_e32 v250, 0x0da24260, v250
	v_max_f32_e32 v168, 0x0da24260, v168
	v_max_f32_e32 v192, 0x0da24260, v192
	v_max_f32_e32 v169, 0x0da24260, v169
	v_mul_f32_e32 v250, v38, v250
	v_mul_f32_e32 v168, v39, v168
	v_mul_f32_e32 v192, v40, v192
	v_mul_f32_e32 v169, v41, v169
	v_cvt_pk_bf16_f32 v168, v250, v168
	v_cvt_pk_bf16_f32 v169, v192, v169
	v_lshlrev_b32_e32 v250, 16, v170
	v_and_b32_e32 v170, 0xffff0000, v170
	v_lshlrev_b32_e32 v192, 16, v171
	v_and_b32_e32 v171, 0xffff0000, v171
	v_max_f32_e32 v250, 0x0da24260, v250
	v_max_f32_e32 v170, 0x0da24260, v170
	v_max_f32_e32 v192, 0x0da24260, v192
	v_max_f32_e32 v171, 0x0da24260, v171
	v_mul_f32_e32 v250, v34, v250
	v_mul_f32_e32 v170, v35, v170
	v_mul_f32_e32 v192, v36, v192
	v_mul_f32_e32 v171, v37, v171
	v_cvt_pk_bf16_f32 v170, v250, v170
	v_cvt_pk_bf16_f32 v171, v192, v171
	global_store_dwordx4 v249, v[168:171], s[92:93] offset:256
	s_waitcnt vmcnt(15)
	v_lshlrev_b32_e32 v250, 16, v172
	v_and_b32_e32 v172, 0xffff0000, v172
	v_lshlrev_b32_e32 v192, 16, v173
	v_and_b32_e32 v173, 0xffff0000, v173
	v_max_f32_e32 v250, 0x0da24260, v250
	v_max_f32_e32 v172, 0x0da24260, v172
	v_max_f32_e32 v192, 0x0da24260, v192
	v_max_f32_e32 v173, 0x0da24260, v173
	v_mul_f32_e32 v250, v30, v250
	v_mul_f32_e32 v172, v31, v172
	v_mul_f32_e32 v192, v32, v192
	v_mul_f32_e32 v173, v33, v173
	v_cvt_pk_bf16_f32 v172, v250, v172
	v_cvt_pk_bf16_f32 v173, v192, v173
	v_lshlrev_b32_e32 v250, 16, v174
	v_and_b32_e32 v174, 0xffff0000, v174
	v_lshlrev_b32_e32 v192, 16, v175
	v_and_b32_e32 v175, 0xffff0000, v175
	v_max_f32_e32 v250, 0x0da24260, v250
	v_max_f32_e32 v174, 0x0da24260, v174
	v_max_f32_e32 v192, 0x0da24260, v192
	v_max_f32_e32 v175, 0x0da24260, v175
	v_mul_f32_e32 v250, v26, v250
	v_mul_f32_e32 v174, v27, v174
	v_mul_f32_e32 v192, v28, v192
	v_mul_f32_e32 v175, v29, v175
	v_cvt_pk_bf16_f32 v174, v250, v174
	v_cvt_pk_bf16_f32 v175, v192, v175
	global_store_dwordx4 v249, v[172:175], s[94:95]
	s_waitcnt vmcnt(15)
	v_lshlrev_b32_e32 v250, 16, v180
	v_and_b32_e32 v180, 0xffff0000, v180
	v_lshlrev_b32_e32 v192, 16, v181
	v_and_b32_e32 v181, 0xffff0000, v181
	v_max_f32_e32 v250, 0x0da24260, v250
	v_max_f32_e32 v180, 0x0da24260, v180
	v_max_f32_e32 v192, 0x0da24260, v192
	v_max_f32_e32 v181, 0x0da24260, v181
	v_mul_f32_e32 v250, v18, v250
	v_mul_f32_e32 v180, v19, v180
	v_mul_f32_e32 v192, v20, v192
	v_mul_f32_e32 v181, v21, v181
	v_cvt_pk_bf16_f32 v180, v250, v180
	v_cvt_pk_bf16_f32 v181, v192, v181
	v_lshlrev_b32_e32 v250, 16, v182
	v_and_b32_e32 v182, 0xffff0000, v182
	v_lshlrev_b32_e32 v192, 16, v183
	v_and_b32_e32 v183, 0xffff0000, v183
	v_max_f32_e32 v250, 0x0da24260, v250
	v_max_f32_e32 v182, 0x0da24260, v182
	v_max_f32_e32 v192, 0x0da24260, v192
	v_max_f32_e32 v183, 0x0da24260, v183
	v_mul_f32_e32 v250, v10, v250
	v_mul_f32_e32 v182, v11, v182
	v_mul_f32_e32 v192, v12, v192
	v_mul_f32_e32 v183, v13, v183
	v_cvt_pk_bf16_f32 v182, v250, v182
	v_cvt_pk_bf16_f32 v183, v192, v183
	global_store_dwordx4 v249, v[180:183], s[94:95] offset:256
	s_waitcnt vmcnt(15)
	v_lshlrev_b32_e32 v250, 16, v184
	v_and_b32_e32 v184, 0xffff0000, v184
	v_lshlrev_b32_e32 v192, 16, v185
	v_and_b32_e32 v185, 0xffff0000, v185
	v_max_f32_e32 v250, 0x0da24260, v250
	v_max_f32_e32 v184, 0x0da24260, v184
	v_max_f32_e32 v192, 0x0da24260, v192
	v_max_f32_e32 v185, 0x0da24260, v185
	v_mul_f32_e32 v250, v22, v250
	v_mul_f32_e32 v184, v23, v184
	v_mul_f32_e32 v192, v24, v192
	v_mul_f32_e32 v185, v25, v185
	v_cvt_pk_bf16_f32 v184, v250, v184
	v_cvt_pk_bf16_f32 v185, v192, v185
	v_lshlrev_b32_e32 v250, 16, v186
	v_and_b32_e32 v186, 0xffff0000, v186
	v_lshlrev_b32_e32 v192, 16, v187
	v_and_b32_e32 v187, 0xffff0000, v187
	v_max_f32_e32 v250, 0x0da24260, v250
	v_max_f32_e32 v186, 0x0da24260, v186
	v_max_f32_e32 v192, 0x0da24260, v192
	v_max_f32_e32 v187, 0x0da24260, v187
	v_mul_f32_e32 v250, v14, v250
	v_mul_f32_e32 v186, v15, v186
	v_mul_f32_e32 v192, v16, v192
	v_mul_f32_e32 v187, v17, v187
	v_cvt_pk_bf16_f32 v186, v250, v186
	v_cvt_pk_bf16_f32 v187, v192, v187
	global_store_dwordx4 v249, v[184:187], s[96:97]
	s_waitcnt vmcnt(15)
	v_lshlrev_b32_e32 v250, 16, v188
	v_and_b32_e32 v188, 0xffff0000, v188
	v_lshlrev_b32_e32 v192, 16, v189
	v_and_b32_e32 v189, 0xffff0000, v189
	v_max_f32_e32 v250, 0x0da24260, v250
	v_max_f32_e32 v188, 0x0da24260, v188
	v_max_f32_e32 v192, 0x0da24260, v192
	v_max_f32_e32 v189, 0x0da24260, v189
	v_mul_f32_e32 v250, v6, v250
	v_mul_f32_e32 v188, v7, v188
	v_mul_f32_e32 v192, v8, v192
	v_mul_f32_e32 v189, v9, v189
	v_cvt_pk_bf16_f32 v188, v250, v188
	v_cvt_pk_bf16_f32 v189, v192, v189
	v_lshlrev_b32_e32 v250, 16, v190
	v_and_b32_e32 v190, 0xffff0000, v190
	v_lshlrev_b32_e32 v192, 16, v191
	v_and_b32_e32 v191, 0xffff0000, v191
	v_max_f32_e32 v250, 0x0da24260, v250
	v_max_f32_e32 v190, 0x0da24260, v190
	v_max_f32_e32 v192, 0x0da24260, v192
	v_max_f32_e32 v191, 0x0da24260, v191
	v_mul_f32_e32 v250, v2, v250
	v_mul_f32_e32 v190, v3, v190
	v_mul_f32_e32 v192, v4, v192
	v_mul_f32_e32 v191, v5, v191
	v_cvt_pk_bf16_f32 v190, v250, v190
	v_cvt_pk_bf16_f32 v191, v192, v191
	global_store_dwordx4 v249, v[188:191], s[96:97] offset:256
